# store widening completed for G/I (dead fragment registers as tuple pool), B zs epilogue, C q-tile epilogue
# speedup vs baseline: 1.0068x; 1.0068x over previous
.LBB0_110:
	s_add_u32 s12, s10, 0x100
	s_addc_u32 s13, s11, 0
	s_add_i32 s37, 0, 0x10000
	v_add_u32_e32 v139, s37, v137
	ds_read_b128 v[140:143], v139
	ds_read_b128 v[144:147], v139 offset:1024
	ds_read_b128 v[148:151], v139 offset:2048
	ds_read_b128 v[152:155], v139 offset:3072
	s_cmp_eq_u32 s36, 40
	s_cselect_b32 s17, s9, s13
	s_cselect_b32 s16, s8, s12
	s_cselect_b32 s15, s5, s35
	s_cselect_b32 s14, s4, s34
	v_lshl_add_u64 v[190:191], s[10:11], 0, v[132:133]
	s_add_i32 m0, s22, 0xc000
	ds_read_b128 v[156:159], v138
	ds_read_b128 v[160:163], v138 offset:1024
	ds_read_b128 v[164:167], v138 offset:2048
	ds_read_b128 v[168:171], v138 offset:3072
	ds_read_b128 v[172:175], v138 offset:4096
	ds_read_b128 v[176:179], v138 offset:5120
	ds_read_b128 v[180:183], v138 offset:6144
	ds_read_b128 v[184:187], v138 offset:7168
	global_load_lds_dwordx4 v[190:191], off
	v_lshl_add_u64 v[190:191], s[10:11], 0, v[134:135]
	s_add_i32 m0, s22, 0xe000
	s_nop 0
	global_load_lds_dwordx4 v[190:191], off
	s_waitcnt lgkmcnt(8)
	s_barrier
	s_waitcnt lgkmcnt(0)
	s_setprio 1
	s_waitcnt lgkmcnt(0)
	v_mfma_f32_16x16x32_bf16 v[124:127], v[140:143], v[156:159], v[124:127]
	v_mfma_f32_16x16x32_bf16 v[120:123], v[148:151], v[156:159], v[120:123]
	v_mfma_f32_16x16x32_bf16 v[116:119], v[140:143], v[164:167], v[116:119]
	v_mfma_f32_16x16x32_bf16 v[108:111], v[148:151], v[164:167], v[108:111]
	v_mfma_f32_16x16x32_bf16 v[100:103], v[140:143], v[172:175], v[100:103]
	v_mfma_f32_16x16x32_bf16 v[92:95], v[148:151], v[172:175], v[92:95]
	v_mfma_f32_16x16x32_bf16 v[84:87], v[140:143], v[180:183], v[84:87]
	v_mfma_f32_16x16x32_bf16 v[76:79], v[148:151], v[180:183], v[76:79]
	v_mfma_f32_16x16x32_bf16 v[124:127], v[144:147], v[160:163], v[124:127]
	v_mfma_f32_16x16x32_bf16 v[120:123], v[152:155], v[160:163], v[120:123]
	v_mfma_f32_16x16x32_bf16 v[116:119], v[144:147], v[168:171], v[116:119]
	v_mfma_f32_16x16x32_bf16 v[108:111], v[152:155], v[168:171], v[108:111]
	v_mfma_f32_16x16x32_bf16 v[100:103], v[144:147], v[176:179], v[100:103]
	v_mfma_f32_16x16x32_bf16 v[92:95], v[152:155], v[176:179], v[92:95]
	v_mfma_f32_16x16x32_bf16 v[84:87], v[144:147], v[184:187], v[84:87]
	v_mfma_f32_16x16x32_bf16 v[76:79], v[152:155], v[184:187], v[76:79]
	s_setprio 0
	s_barrier
	s_add_i32 s38, 0, 0x14000
	s_add_i32 s10, s37, s21
	v_add_u32_e32 v139, s38, v137
	v_lshl_add_u64 v[202:203], s[14:15], 0, v[130:131]
	s_mov_b32 m0, s10
	ds_read_b128 v[190:193], v139
	ds_read_b128 v[194:197], v139 offset:1024
	ds_read_b128 v[198:201], v139 offset:2048
	ds_read_b128 v[216:219], v139 offset:3072
	global_load_lds_dwordx4 v[202:203], off
	v_lshl_add_u64 v[220:221], s[14:15], 0, v[128:129]
	s_add_i32 m0, s10, 0x2000
	s_nop 0
	global_load_lds_dwordx4 v[220:221], off
	s_barrier
	s_waitcnt lgkmcnt(0)
	s_setprio 1
	s_waitcnt lgkmcnt(0)
	v_mfma_f32_16x16x32_bf16 v[112:115], v[190:193], v[156:159], v[112:115]
	v_mfma_f32_16x16x32_bf16 v[104:107], v[198:201], v[156:159], v[104:107]
	v_mfma_f32_16x16x32_bf16 v[96:99], v[190:193], v[164:167], v[96:99]
	v_mfma_f32_16x16x32_bf16 v[88:91], v[198:201], v[164:167], v[88:91]
	v_mfma_f32_16x16x32_bf16 v[80:83], v[190:193], v[172:175], v[80:83]
	v_mfma_f32_16x16x32_bf16 v[72:75], v[198:201], v[172:175], v[72:75]
	v_mfma_f32_16x16x32_bf16 v[68:71], v[190:193], v[180:183], v[68:71]
	v_mfma_f32_16x16x32_bf16 v[64:67], v[198:201], v[180:183], v[64:67]
	v_mfma_f32_16x16x32_bf16 v[112:115], v[194:197], v[160:163], v[112:115]
	v_mfma_f32_16x16x32_bf16 v[104:107], v[216:219], v[160:163], v[104:107]
	v_mfma_f32_16x16x32_bf16 v[96:99], v[194:197], v[168:171], v[96:99]
	v_mfma_f32_16x16x32_bf16 v[88:91], v[216:219], v[168:171], v[88:91]
	v_mfma_f32_16x16x32_bf16 v[80:83], v[194:197], v[176:179], v[80:83]
	v_mfma_f32_16x16x32_bf16 v[72:75], v[216:219], v[176:179], v[72:75]
	v_mfma_f32_16x16x32_bf16 v[68:71], v[194:197], v[184:187], v[68:71]
	v_mfma_f32_16x16x32_bf16 v[64:67], v[216:219], v[184:187], v[64:67]
	s_setprio 0
	s_mov_b32 m0, s22
	v_lshl_add_u64 v[222:223], s[16:17], 0, v[130:131]
	s_barrier
	ds_read_b128 v[156:159], v138 offset:16384
	ds_read_b128 v[160:163], v138 offset:17408
	ds_read_b128 v[164:167], v138 offset:18432
	ds_read_b128 v[168:171], v138 offset:19456
	ds_read_b128 v[172:175], v138 offset:20480
	ds_read_b128 v[176:179], v138 offset:21504
	ds_read_b128 v[180:183], v138 offset:22528
	ds_read_b128 v[184:187], v138 offset:23552
	global_load_lds_dwordx4 v[222:223], off
	v_lshl_add_u64 v[224:225], s[16:17], 0, v[128:129]
	s_mov_b32 m0, s23
	s_nop 0
	global_load_lds_dwordx4 v[224:225], off
	s_barrier
	s_waitcnt lgkmcnt(0)
	s_setprio 1
	s_waitcnt lgkmcnt(0)
	v_mfma_f32_16x16x32_bf16 v[60:63], v[140:143], v[156:159], v[60:63]
	v_mfma_f32_16x16x32_bf16 v[56:59], v[148:151], v[156:159], v[56:59]
	v_mfma_f32_16x16x32_bf16 v[52:55], v[140:143], v[164:167], v[52:55]
	v_mfma_f32_16x16x32_bf16 v[44:47], v[148:151], v[164:167], v[44:47]
	v_mfma_f32_16x16x32_bf16 v[36:39], v[140:143], v[172:175], v[36:39]
	v_mfma_f32_16x16x32_bf16 v[28:31], v[148:151], v[172:175], v[28:31]
	v_mfma_f32_16x16x32_bf16 v[20:23], v[140:143], v[180:183], v[20:23]
	v_mfma_f32_16x16x32_bf16 v[12:15], v[148:151], v[180:183], v[12:15]
	v_mfma_f32_16x16x32_bf16 v[60:63], v[144:147], v[160:163], v[60:63]
	v_mfma_f32_16x16x32_bf16 v[56:59], v[152:155], v[160:163], v[56:59]
	v_mfma_f32_16x16x32_bf16 v[52:55], v[144:147], v[168:171], v[52:55]
	v_mfma_f32_16x16x32_bf16 v[44:47], v[152:155], v[168:171], v[44:47]
	v_mfma_f32_16x16x32_bf16 v[36:39], v[144:147], v[176:179], v[36:39]
	v_mfma_f32_16x16x32_bf16 v[28:31], v[152:155], v[176:179], v[28:31]
	v_mfma_f32_16x16x32_bf16 v[20:23], v[144:147], v[184:187], v[20:23]
	v_mfma_f32_16x16x32_bf16 v[12:15], v[152:155], v[184:187], v[12:15]
	s_setprio 0
	s_barrier
	s_add_u32 s10, s14, 0xb0000
	s_addc_u32 s11, s15, 0
	s_add_i32 s37, s38, s21
	v_lshl_add_u64 v[140:141], s[10:11], 0, v[130:131]
	s_mov_b32 m0, s37
	s_nop 0
	global_load_lds_dwordx4 v[140:141], off
	v_lshl_add_u64 v[140:141], s[10:11], 0, v[128:129]
	s_add_i32 m0, s37, 0x2000
	s_nop 0
	global_load_lds_dwordx4 v[140:141], off
	s_waitcnt vmcnt(6)
	s_barrier
	s_setprio 1
	v_mfma_f32_16x16x32_bf16 v[48:51], v[190:193], v[156:159], v[48:51]
	v_mfma_f32_16x16x32_bf16 v[40:43], v[198:201], v[156:159], v[40:43]
	v_mfma_f32_16x16x32_bf16 v[32:35], v[190:193], v[164:167], v[32:35]
	v_mfma_f32_16x16x32_bf16 v[24:27], v[198:201], v[164:167], v[24:27]
	v_mfma_f32_16x16x32_bf16 v[16:19], v[190:193], v[172:175], v[16:19]
	v_mfma_f32_16x16x32_bf16 v[8:11], v[198:201], v[172:175], v[8:11]
	v_mfma_f32_16x16x32_bf16 v[4:7], v[190:193], v[180:183], v[4:7]
	v_mfma_f32_16x16x32_bf16 v[0:3], v[198:201], v[180:183], v[0:3]
	v_mfma_f32_16x16x32_bf16 v[48:51], v[194:197], v[160:163], v[48:51]
	v_mfma_f32_16x16x32_bf16 v[40:43], v[216:219], v[160:163], v[40:43]
	v_mfma_f32_16x16x32_bf16 v[32:35], v[194:197], v[168:171], v[32:35]
	v_mfma_f32_16x16x32_bf16 v[24:27], v[216:219], v[168:171], v[24:27]
	v_mfma_f32_16x16x32_bf16 v[16:19], v[194:197], v[176:179], v[16:19]
	v_mfma_f32_16x16x32_bf16 v[8:11], v[216:219], v[176:179], v[8:11]
	v_mfma_f32_16x16x32_bf16 v[4:7], v[194:197], v[184:187], v[4:7]
	v_mfma_f32_16x16x32_bf16 v[0:3], v[216:219], v[184:187], v[0:3]
	s_setprio 0
	s_add_i32 s37, 0, 0x18000
	v_add_u32_e32 v139, s37, v137
	s_barrier
	ds_read_b128 v[140:143], v139
	ds_read_b128 v[144:147], v139 offset:1024
	ds_read_b128 v[148:151], v139 offset:2048
	ds_read_b128 v[152:155], v139 offset:3072
	s_add_u32 s10, s16, 0xb0000
	s_addc_u32 s11, s17, 0
	s_mov_b32 m0, s24
	v_lshl_add_u64 v[190:191], s[10:11], 0, v[130:131]
	ds_read_b128 v[156:159], v138 offset:32768
	ds_read_b128 v[160:163], v138 offset:33792
	ds_read_b128 v[164:167], v138 offset:34816
	ds_read_b128 v[168:171], v138 offset:35840
	ds_read_b128 v[172:175], v138 offset:36864
	ds_read_b128 v[176:179], v138 offset:37888
	ds_read_b128 v[180:183], v138 offset:38912
	ds_read_b128 v[184:187], v138 offset:39936
	global_load_lds_dwordx4 v[190:191], off
	v_lshl_add_u64 v[190:191], s[10:11], 0, v[128:129]
	s_mov_b32 m0, s25
	s_nop 0
	global_load_lds_dwordx4 v[190:191], off
	s_waitcnt lgkmcnt(8)
	s_barrier
	s_waitcnt lgkmcnt(0)
	s_setprio 1
	s_waitcnt lgkmcnt(0)
	v_mfma_f32_16x16x32_bf16 v[124:127], v[140:143], v[156:159], v[124:127]
	v_mfma_f32_16x16x32_bf16 v[120:123], v[148:151], v[156:159], v[120:123]
	v_mfma_f32_16x16x32_bf16 v[116:119], v[140:143], v[164:167], v[116:119]
	v_mfma_f32_16x16x32_bf16 v[108:111], v[148:151], v[164:167], v[108:111]
	v_mfma_f32_16x16x32_bf16 v[100:103], v[140:143], v[172:175], v[100:103]
	v_mfma_f32_16x16x32_bf16 v[92:95], v[148:151], v[172:175], v[92:95]
	v_mfma_f32_16x16x32_bf16 v[84:87], v[140:143], v[180:183], v[84:87]
	v_mfma_f32_16x16x32_bf16 v[76:79], v[148:151], v[180:183], v[76:79]
	v_mfma_f32_16x16x32_bf16 v[124:127], v[144:147], v[160:163], v[124:127]
	v_mfma_f32_16x16x32_bf16 v[120:123], v[152:155], v[160:163], v[120:123]
	v_mfma_f32_16x16x32_bf16 v[116:119], v[144:147], v[168:171], v[116:119]
	v_mfma_f32_16x16x32_bf16 v[108:111], v[152:155], v[168:171], v[108:111]
	v_mfma_f32_16x16x32_bf16 v[100:103], v[144:147], v[176:179], v[100:103]
	v_mfma_f32_16x16x32_bf16 v[92:95], v[152:155], v[176:179], v[92:95]
	v_mfma_f32_16x16x32_bf16 v[84:87], v[144:147], v[184:187], v[84:87]
	v_mfma_f32_16x16x32_bf16 v[76:79], v[152:155], v[184:187], v[76:79]
	s_setprio 0
	s_barrier
	s_add_i32 s16, 0, 0x1c000
	s_add_i32 s10, s37, s21
	v_add_u32_e32 v139, s16, v137
	v_lshl_add_u64 v[202:203], v[202:203], 0, s[92:93]
	s_mov_b32 m0, s10
	ds_read_b128 v[190:193], v139
	ds_read_b128 v[194:197], v139 offset:1024
	ds_read_b128 v[198:201], v139 offset:2048
	ds_read_b128 v[216:219], v139 offset:3072
	global_load_lds_dwordx4 v[202:203], off
	v_lshl_add_u64 v[202:203], v[220:221], 0, s[92:93]
	s_add_i32 m0, s10, 0x2000
	s_nop 0
	global_load_lds_dwordx4 v[202:203], off
	s_barrier
	s_waitcnt lgkmcnt(0)
	s_setprio 1
	s_waitcnt lgkmcnt(0)
	v_mfma_f32_16x16x32_bf16 v[112:115], v[190:193], v[156:159], v[112:115]
	v_mfma_f32_16x16x32_bf16 v[104:107], v[198:201], v[156:159], v[104:107]
	v_mfma_f32_16x16x32_bf16 v[96:99], v[190:193], v[164:167], v[96:99]
	v_mfma_f32_16x16x32_bf16 v[88:91], v[198:201], v[164:167], v[88:91]
	v_mfma_f32_16x16x32_bf16 v[80:83], v[190:193], v[172:175], v[80:83]
	v_mfma_f32_16x16x32_bf16 v[72:75], v[198:201], v[172:175], v[72:75]
	v_mfma_f32_16x16x32_bf16 v[68:71], v[190:193], v[180:183], v[68:71]
	v_mfma_f32_16x16x32_bf16 v[64:67], v[198:201], v[180:183], v[64:67]
	v_mfma_f32_16x16x32_bf16 v[112:115], v[194:197], v[160:163], v[112:115]
	v_mfma_f32_16x16x32_bf16 v[104:107], v[216:219], v[160:163], v[104:107]
	v_mfma_f32_16x16x32_bf16 v[96:99], v[194:197], v[168:171], v[96:99]
	v_mfma_f32_16x16x32_bf16 v[88:91], v[216:219], v[168:171], v[88:91]
	v_mfma_f32_16x16x32_bf16 v[80:83], v[194:197], v[176:179], v[80:83]
	v_mfma_f32_16x16x32_bf16 v[72:75], v[216:219], v[176:179], v[72:75]
	v_mfma_f32_16x16x32_bf16 v[68:71], v[194:197], v[184:187], v[68:71]
	v_mfma_f32_16x16x32_bf16 v[64:67], v[216:219], v[184:187], v[64:67]
	s_setprio 0
	s_mov_b32 m0, s26
	v_lshl_add_u64 v[202:203], v[222:223], 0, s[92:93]
	s_barrier
	ds_read_b128 v[156:159], v138 offset:49152
	ds_read_b128 v[160:163], v138 offset:50176
	ds_read_b128 v[164:167], v138 offset:51200
	ds_read_b128 v[168:171], v138 offset:52224
	ds_read_b128 v[172:175], v138 offset:53248
	ds_read_b128 v[176:179], v138 offset:54272
	ds_read_b128 v[180:183], v138 offset:55296
	ds_read_b128 v[184:187], v138 offset:56320
	global_load_lds_dwordx4 v[202:203], off
	v_lshl_add_u64 v[202:203], v[224:225], 0, s[92:93]
	s_mov_b32 m0, s27
	s_nop 0
	global_load_lds_dwordx4 v[202:203], off
	s_barrier
	s_waitcnt lgkmcnt(0)
	s_setprio 1
	s_waitcnt lgkmcnt(0)
	v_mfma_f32_16x16x32_bf16 v[60:63], v[140:143], v[156:159], v[60:63]
	v_mfma_f32_16x16x32_bf16 v[56:59], v[148:151], v[156:159], v[56:59]
	v_mfma_f32_16x16x32_bf16 v[52:55], v[140:143], v[164:167], v[52:55]
	v_mfma_f32_16x16x32_bf16 v[44:47], v[148:151], v[164:167], v[44:47]
	v_mfma_f32_16x16x32_bf16 v[36:39], v[140:143], v[172:175], v[36:39]
	v_mfma_f32_16x16x32_bf16 v[28:31], v[148:151], v[172:175], v[28:31]
	v_mfma_f32_16x16x32_bf16 v[20:23], v[140:143], v[180:183], v[20:23]
	v_mfma_f32_16x16x32_bf16 v[12:15], v[148:151], v[180:183], v[12:15]
	v_mfma_f32_16x16x32_bf16 v[60:63], v[144:147], v[160:163], v[60:63]
	v_mfma_f32_16x16x32_bf16 v[56:59], v[152:155], v[160:163], v[56:59]
	v_mfma_f32_16x16x32_bf16 v[52:55], v[144:147], v[168:171], v[52:55]
	v_mfma_f32_16x16x32_bf16 v[44:47], v[152:155], v[168:171], v[44:47]
	v_mfma_f32_16x16x32_bf16 v[36:39], v[144:147], v[176:179], v[36:39]
	v_mfma_f32_16x16x32_bf16 v[28:31], v[152:155], v[176:179], v[28:31]
	v_mfma_f32_16x16x32_bf16 v[20:23], v[144:147], v[184:187], v[20:23]
	v_mfma_f32_16x16x32_bf16 v[12:15], v[152:155], v[184:187], v[12:15]
	s_setprio 0
	s_barrier
	s_add_u32 s10, s14, 0xb0080
	s_addc_u32 s11, s15, 0
	s_add_i32 s14, s16, s21
	v_lshl_add_u64 v[140:141], s[10:11], 0, v[130:131]
	s_mov_b32 m0, s14
	s_nop 0
	global_load_lds_dwordx4 v[140:141], off
	v_lshl_add_u64 v[140:141], s[10:11], 0, v[128:129]
	s_add_i32 m0, s14, 0x2000
	s_nop 0
	global_load_lds_dwordx4 v[140:141], off
	s_waitcnt vmcnt(6)
	s_barrier
	s_setprio 1
	v_mfma_f32_16x16x32_bf16 v[48:51], v[190:193], v[156:159], v[48:51]
	v_mfma_f32_16x16x32_bf16 v[40:43], v[198:201], v[156:159], v[40:43]
	v_mfma_f32_16x16x32_bf16 v[32:35], v[190:193], v[164:167], v[32:35]
	v_mfma_f32_16x16x32_bf16 v[24:27], v[198:201], v[164:167], v[24:27]
	v_mfma_f32_16x16x32_bf16 v[16:19], v[190:193], v[172:175], v[16:19]
	v_mfma_f32_16x16x32_bf16 v[8:11], v[198:201], v[172:175], v[8:11]
	v_mfma_f32_16x16x32_bf16 v[4:7], v[190:193], v[180:183], v[4:7]
	v_mfma_f32_16x16x32_bf16 v[0:3], v[198:201], v[180:183], v[0:3]
	v_mfma_f32_16x16x32_bf16 v[48:51], v[194:197], v[160:163], v[48:51]
	v_mfma_f32_16x16x32_bf16 v[40:43], v[216:219], v[160:163], v[40:43]
	v_mfma_f32_16x16x32_bf16 v[32:35], v[194:197], v[168:171], v[32:35]
	v_mfma_f32_16x16x32_bf16 v[24:27], v[216:219], v[168:171], v[24:27]
	v_mfma_f32_16x16x32_bf16 v[16:19], v[194:197], v[176:179], v[16:19]
	v_mfma_f32_16x16x32_bf16 v[8:11], v[216:219], v[176:179], v[8:11]
	v_mfma_f32_16x16x32_bf16 v[4:7], v[194:197], v[184:187], v[4:7]
	v_mfma_f32_16x16x32_bf16 v[0:3], v[216:219], v[184:187], v[0:3]
	s_setprio 0
	s_add_i32 s36, s36, 2
	s_add_u32 s34, s34, 0x100
	s_addc_u32 s35, s35, 0
	s_cmp_gt_u32 s36, 41
	s_mov_b64 s[10:11], s[12:13]
	s_barrier
	s_cbranch_scc0 .LBB0_110
	v_lshl_add_u32 v140, s33, 8, v136
	s_lshl_b32 s10, s31, 8
	v_ashrrev_i32_e32 v141, 31, v140
	v_readlane_b32 s12, v253, 0
	s_ashr_i32 s11, s10, 31
	v_lshlrev_b64 v[142:143], 11, v[140:141]
	v_readlane_b32 s13, v253, 1
	s_lshl_b64 s[10:11], s[10:11], 1
	v_cvt_pk_bf16_f32 v104, v104, v105
	v_lshl_add_u64 v[142:143], s[12:13], 0, v[142:143]
	v_lshl_add_u64 v[142:143], v[142:143], 0, s[10:11]
	v_lshl_add_u64 v[142:143], v[142:143], 0, s[0:1]
	v_lshl_add_u64 v[142:143], v[142:143], 0, v[188:189]
	v_cvt_pk_bf16_f32 v105, v106, v107
	v_and_b32_e32 v230, 16, v204
	v_lshrrev_b32_e32 v231, 1, v230
	v_add_u32_e32 v230, v230, v231
	v_mov_b32_e32 v231, v189
	v_mov_b64_e32 v[234:235], v[104:105]
	v_or_b32_e32 v104, 16, v140
	v_ashrrev_i32_e32 v105, 31, v104
	v_lshlrev_b64 v[104:105], 11, v[104:105]
	v_lshl_add_u64 v[104:105], s[12:13], 0, v[104:105]
	v_lshl_add_u64 v[104:105], v[104:105], 0, s[10:11]
	v_lshl_add_u64 v[104:105], v[104:105], 0, s[0:1]
	v_lshl_add_u64 v[104:105], v[104:105], 0, v[188:189]
	v_cvt_pk_bf16_f32 v88, v88, v89
	v_cvt_pk_bf16_f32 v89, v90, v91
	v_mov_b64_e32 v[238:239], v[88:89]
	v_or_b32_e32 v88, 32, v140
	v_ashrrev_i32_e32 v89, 31, v88
	v_lshlrev_b64 v[88:89], 11, v[88:89]
	v_lshl_add_u64 v[88:89], s[12:13], 0, v[88:89]
	v_lshl_add_u64 v[88:89], v[88:89], 0, s[10:11]
	v_lshl_add_u64 v[88:89], v[88:89], 0, s[0:1]
	v_lshl_add_u64 v[88:89], v[88:89], 0, v[188:189]
	v_cvt_pk_bf16_f32 v72, v72, v73
	v_cvt_pk_bf16_f32 v73, v74, v75
	v_mov_b64_e32 v[242:243], v[72:73]
	v_or_b32_e32 v72, 48, v140
	v_ashrrev_i32_e32 v73, 31, v72
	v_lshlrev_b64 v[72:73], 11, v[72:73]
	v_lshl_add_u64 v[72:73], s[12:13], 0, v[72:73]
	v_lshl_add_u64 v[72:73], v[72:73], 0, s[10:11]
	v_lshl_add_u64 v[72:73], v[72:73], 0, s[0:1]
	v_lshl_add_u64 v[72:73], v[72:73], 0, v[188:189]
	v_cvt_pk_bf16_f32 v64, v64, v65
	v_cvt_pk_bf16_f32 v65, v66, v67
	v_mov_b64_e32 v[246:247], v[64:65]
	v_add_u32_e32 v64, 0x80, v140
	v_ashrrev_i32_e32 v65, 31, v64
	v_lshlrev_b64 v[64:65], 11, v[64:65]
	v_lshl_add_u64 v[64:65], s[12:13], 0, v[64:65]
	v_lshl_add_u64 v[64:65], v[64:65], 0, s[10:11]
	v_lshl_add_u64 v[64:65], v[64:65], 0, s[0:1]
	v_lshl_add_u64 v[64:65], v[64:65], 0, v[188:189]
	v_cvt_pk_bf16_f32 v40, v40, v41
	v_cvt_pk_bf16_f32 v41, v42, v43
	v_mov_b64_e32 v[150:151], v[40:41]
	v_add_u32_e32 v40, 0x90, v140
	v_ashrrev_i32_e32 v41, 31, v40
	v_lshlrev_b64 v[40:41], 11, v[40:41]
	v_lshl_add_u64 v[40:41], s[12:13], 0, v[40:41]
	v_lshl_add_u64 v[40:41], v[40:41], 0, s[10:11]
	v_lshl_add_u64 v[40:41], v[40:41], 0, s[0:1]
	v_lshl_add_u64 v[40:41], v[40:41], 0, v[188:189]
	v_cvt_pk_bf16_f32 v24, v24, v25
	v_cvt_pk_bf16_f32 v25, v26, v27
	v_mov_b64_e32 v[154:155], v[24:25]
	v_add_u32_e32 v24, 0xa0, v140
	v_ashrrev_i32_e32 v25, 31, v24
	v_lshlrev_b64 v[24:25], 11, v[24:25]
	v_lshl_add_u64 v[24:25], s[12:13], 0, v[24:25]
	v_lshl_add_u64 v[24:25], v[24:25], 0, s[10:11]
	v_lshl_add_u64 v[24:25], v[24:25], 0, s[0:1]
	v_lshl_add_u64 v[24:25], v[24:25], 0, v[188:189]
	v_cvt_pk_bf16_f32 v8, v8, v9
	v_cvt_pk_bf16_f32 v9, v10, v11
	v_mov_b64_e32 v[158:159], v[8:9]
	v_add_u32_e32 v8, 0xb0, v140
	v_ashrrev_i32_e32 v9, 31, v8
	v_lshlrev_b64 v[8:9], 11, v[8:9]
	v_lshl_add_u64 v[8:9], s[12:13], 0, v[8:9]
	v_lshl_add_u64 v[8:9], v[8:9], 0, s[10:11]
	v_lshl_add_u64 v[8:9], v[8:9], 0, s[0:1]
	v_cvt_pk_bf16_f32 v106, v116, v117
	v_cvt_pk_bf16_f32 v107, v118, v119
	v_cvt_pk_bf16_f32 v90, v100, v101
	v_cvt_pk_bf16_f32 v91, v102, v103
	v_cvt_pk_bf16_f32 v74, v84, v85
	v_cvt_pk_bf16_f32 v75, v86, v87
	v_cvt_pk_bf16_f32 v42, v52, v53
	v_cvt_pk_bf16_f32 v43, v54, v55
	v_cvt_pk_bf16_f32 v26, v36, v37
	v_cvt_pk_bf16_f32 v27, v38, v39
	v_lshl_add_u64 v[8:9], v[8:9], 0, v[188:189]
	v_cvt_pk_bf16_f32 v10, v20, v21
	v_cvt_pk_bf16_f32 v11, v22, v23
	v_cvt_pk_bf16_f32 v124, v124, v125
	v_cvt_pk_bf16_f32 v125, v126, v127
	v_cvt_pk_bf16_f32 v120, v120, v121
	v_cvt_pk_bf16_f32 v121, v122, v123
	v_cvt_pk_bf16_f32 v112, v112, v113
	v_cvt_pk_bf16_f32 v113, v114, v115
	v_mov_b64_e32 v[160:161], v[106:107]
	v_cvt_pk_bf16_f32 v106, v108, v109
	v_cvt_pk_bf16_f32 v107, v110, v111
	v_cvt_pk_bf16_f32 v96, v96, v97
	v_cvt_pk_bf16_f32 v97, v98, v99
	v_mov_b64_e32 v[164:165], v[90:91]
	v_cvt_pk_bf16_f32 v90, v92, v93
	v_cvt_pk_bf16_f32 v91, v94, v95
	v_cvt_pk_bf16_f32 v80, v80, v81
	v_cvt_pk_bf16_f32 v81, v82, v83
	v_mov_b64_e32 v[168:169], v[74:75]
	v_cvt_pk_bf16_f32 v74, v76, v77
	v_cvt_pk_bf16_f32 v75, v78, v79
	v_cvt_pk_bf16_f32 v68, v68, v69
	v_cvt_pk_bf16_f32 v69, v70, v71
	v_cvt_pk_bf16_f32 v60, v60, v61
	v_cvt_pk_bf16_f32 v61, v62, v63
	v_cvt_pk_bf16_f32 v56, v56, v57
	v_cvt_pk_bf16_f32 v57, v58, v59
	v_cvt_pk_bf16_f32 v48, v48, v49
	v_cvt_pk_bf16_f32 v49, v50, v51
	v_mov_b64_e32 v[172:173], v[42:43]
	v_cvt_pk_bf16_f32 v42, v44, v45
	v_cvt_pk_bf16_f32 v43, v46, v47
	v_cvt_pk_bf16_f32 v32, v32, v33
	v_cvt_pk_bf16_f32 v33, v34, v35
	v_mov_b64_e32 v[176:177], v[26:27]
	v_cvt_pk_bf16_f32 v26, v28, v29
	v_cvt_pk_bf16_f32 v27, v30, v31
	v_cvt_pk_bf16_f32 v16, v16, v17
	v_cvt_pk_bf16_f32 v17, v18, v19
	v_mov_b64_e32 v[180:181], v[10:11]
	v_cvt_pk_bf16_f32 v10, v12, v13
	v_cvt_pk_bf16_f32 v11, v14, v15
	v_cvt_pk_bf16_f32 v4, v4, v5
	v_cvt_pk_bf16_f32 v5, v6, v7
	v_cvt_pk_bf16_f32 v0, v0, v1
	v_cvt_pk_bf16_f32 v1, v2, v3
	s_and_b64 vcc, exec, s[2:3]
	s_mov_b32 s31, s29
	s_mov_b32 s33, s30
	s_mov_b64 s[12:13], s[4:5]
	s_mov_b64 s[10:11], s[8:9]
	global_store_dwordx2 v[142:143], v[124:125], off
	global_store_dwordx2 v[142:143], v[120:121], off offset:32
	v_mov_b64_e32 v[232:233], v[112:113]
	s_nop 1
	v_permlane16_swap_b32 v232, v234
	v_permlane16_swap_b32 v233, v235
	v_lshl_add_u64 v[248:249], v[142:143], 0, v[230:231]
	global_store_dwordx4 v[248:249], v[232:235], off offset:256
	s_nop 1
	v_mov_b64_e32 v[162:163], v[106:107]
	s_nop 1
	v_permlane16_swap_b32 v160, v162
	v_permlane16_swap_b32 v161, v163
	v_lshl_add_u64 v[248:249], v[104:105], 0, v[230:231]
	global_store_dwordx4 v[248:249], v[160:163], off
	s_nop 1
	v_mov_b64_e32 v[236:237], v[96:97]
	s_nop 1
	v_permlane16_swap_b32 v236, v238
	v_permlane16_swap_b32 v237, v239
	v_lshl_add_u64 v[248:249], v[104:105], 0, v[230:231]
	global_store_dwordx4 v[248:249], v[236:239], off offset:256
	s_nop 1
	v_mov_b64_e32 v[166:167], v[90:91]
	s_nop 1
	v_permlane16_swap_b32 v164, v166
	v_permlane16_swap_b32 v165, v167
	v_lshl_add_u64 v[248:249], v[88:89], 0, v[230:231]
	global_store_dwordx4 v[248:249], v[164:167], off
	s_nop 1
	v_mov_b64_e32 v[240:241], v[80:81]
	s_nop 1
	v_permlane16_swap_b32 v240, v242
	v_permlane16_swap_b32 v241, v243
	v_lshl_add_u64 v[248:249], v[88:89], 0, v[230:231]
	global_store_dwordx4 v[248:249], v[240:243], off offset:256
	s_nop 1
	v_mov_b64_e32 v[170:171], v[74:75]
	s_nop 1
	v_permlane16_swap_b32 v168, v170
	v_permlane16_swap_b32 v169, v171
	v_lshl_add_u64 v[248:249], v[72:73], 0, v[230:231]
	global_store_dwordx4 v[248:249], v[168:171], off
	s_nop 1
	v_mov_b64_e32 v[244:245], v[68:69]
	s_nop 1
	v_permlane16_swap_b32 v244, v246
	v_permlane16_swap_b32 v245, v247
	v_lshl_add_u64 v[248:249], v[72:73], 0, v[230:231]
	global_store_dwordx4 v[248:249], v[244:247], off offset:256
	s_nop 1
	v_mov_b64_e32 v[232:233], v[60:61]
	v_mov_b64_e32 v[234:235], v[56:57]
	s_nop 1
	v_permlane16_swap_b32 v232, v234
	v_permlane16_swap_b32 v233, v235
	v_lshl_add_u64 v[248:249], v[64:65], 0, v[230:231]
	global_store_dwordx4 v[248:249], v[232:235], off
	s_nop 1
	v_mov_b64_e32 v[148:149], v[48:49]
	s_nop 1
	v_permlane16_swap_b32 v148, v150
	v_permlane16_swap_b32 v149, v151
	v_lshl_add_u64 v[248:249], v[64:65], 0, v[230:231]
	global_store_dwordx4 v[248:249], v[148:151], off offset:256
	s_nop 1
	v_mov_b64_e32 v[174:175], v[42:43]
	s_nop 1
	v_permlane16_swap_b32 v172, v174
	v_permlane16_swap_b32 v173, v175
	v_lshl_add_u64 v[248:249], v[40:41], 0, v[230:231]
	global_store_dwordx4 v[248:249], v[172:175], off
	s_nop 1
	v_mov_b64_e32 v[152:153], v[32:33]
	s_nop 1
	v_permlane16_swap_b32 v152, v154
	v_permlane16_swap_b32 v153, v155
	v_lshl_add_u64 v[248:249], v[40:41], 0, v[230:231]
	global_store_dwordx4 v[248:249], v[152:155], off offset:256
	s_nop 1
	v_mov_b64_e32 v[178:179], v[26:27]
	s_nop 1
	v_permlane16_swap_b32 v176, v178
	v_permlane16_swap_b32 v177, v179
	v_lshl_add_u64 v[248:249], v[24:25], 0, v[230:231]
	global_store_dwordx4 v[248:249], v[176:179], off
	s_nop 1
	v_mov_b64_e32 v[156:157], v[16:17]
	s_nop 1
	v_permlane16_swap_b32 v156, v158
	v_permlane16_swap_b32 v157, v159
	v_lshl_add_u64 v[248:249], v[24:25], 0, v[230:231]
	global_store_dwordx4 v[248:249], v[156:159], off offset:256
	s_nop 1
	v_mov_b64_e32 v[182:183], v[10:11]
	s_nop 1
	v_permlane16_swap_b32 v180, v182
	v_permlane16_swap_b32 v181, v183
	v_lshl_add_u64 v[248:249], v[8:9], 0, v[230:231]
	global_store_dwordx4 v[248:249], v[180:183], off
	s_nop 1
	v_mov_b64_e32 v[232:233], v[4:5]
	v_mov_b64_e32 v[234:235], v[0:1]
	s_nop 1
	v_permlane16_swap_b32 v232, v234
	v_permlane16_swap_b32 v233, v235
	v_lshl_add_u64 v[248:249], v[8:9], 0, v[230:231]
	global_store_dwordx4 v[248:249], v[232:235], off offset:256
	s_nop 1
	s_cbranch_vccz .LBB0_103
	s_waitcnt vmcnt(0)
	s_cmpk_gt_u32 s18, 0xff
	s_mov_b32 s28, 0x8000
	s_movk_i32 s29, 0xc0
	s_mov_b32 s30, 0x800000
	s_movk_i32 s31, 0x7fff
	s_movk_i32 s33, 0x1800
	s_cbranch_scc1 .LBB0_114
	s_barrier

.LBB0_150:
	s_add_u32 s16, s14, 0xfffc0080
	s_addc_u32 s17, s15, -1
	s_add_i32 s39, 0, 0x10000
	v_add_u32_e32 v139, s39, v137
	ds_read_b128 v[140:143], v139
	ds_read_b128 v[144:147], v139 offset:1024
	ds_read_b128 v[148:151], v139 offset:2048
	ds_read_b128 v[152:155], v139 offset:3072
	s_cmp_eq_u32 s38, 12
	s_cselect_b32 s19, s3, s17
	s_cselect_b32 s18, s34, s16
	s_cselect_b32 s17, s5, s37
	s_cselect_b32 s16, s35, s36
	v_lshl_add_u64 v[190:191], s[14:15], 0, v[132:133]
	s_add_i32 m0, s24, 0xc000
	ds_read_b128 v[156:159], v138
	ds_read_b128 v[160:163], v138 offset:1024
	ds_read_b128 v[164:167], v138 offset:2048
	ds_read_b128 v[168:171], v138 offset:3072
	ds_read_b128 v[172:175], v138 offset:4096
	ds_read_b128 v[176:179], v138 offset:5120
	ds_read_b128 v[180:183], v138 offset:6144
	ds_read_b128 v[184:187], v138 offset:7168
	global_load_lds_dwordx4 v[190:191], off
	v_lshl_add_u64 v[190:191], s[14:15], 0, v[134:135]
	s_add_i32 m0, s24, 0xe000
	s_nop 0
	global_load_lds_dwordx4 v[190:191], off
	s_waitcnt lgkmcnt(8)
	s_barrier
	s_waitcnt lgkmcnt(0)
	s_setprio 1
	s_waitcnt lgkmcnt(0)
	v_mfma_f32_16x16x32_bf16 v[124:127], v[140:143], v[156:159], v[124:127]
	v_mfma_f32_16x16x32_bf16 v[120:123], v[148:151], v[156:159], v[120:123]
	v_mfma_f32_16x16x32_bf16 v[116:119], v[140:143], v[164:167], v[116:119]
	v_mfma_f32_16x16x32_bf16 v[108:111], v[148:151], v[164:167], v[108:111]
	v_mfma_f32_16x16x32_bf16 v[100:103], v[140:143], v[172:175], v[100:103]
	v_mfma_f32_16x16x32_bf16 v[92:95], v[148:151], v[172:175], v[92:95]
	v_mfma_f32_16x16x32_bf16 v[84:87], v[140:143], v[180:183], v[84:87]
	v_mfma_f32_16x16x32_bf16 v[76:79], v[148:151], v[180:183], v[76:79]
	v_mfma_f32_16x16x32_bf16 v[124:127], v[144:147], v[160:163], v[124:127]
	v_mfma_f32_16x16x32_bf16 v[120:123], v[152:155], v[160:163], v[120:123]
	v_mfma_f32_16x16x32_bf16 v[116:119], v[144:147], v[168:171], v[116:119]
	v_mfma_f32_16x16x32_bf16 v[108:111], v[152:155], v[168:171], v[108:111]
	v_mfma_f32_16x16x32_bf16 v[100:103], v[144:147], v[176:179], v[100:103]
	v_mfma_f32_16x16x32_bf16 v[92:95], v[152:155], v[176:179], v[92:95]
	v_mfma_f32_16x16x32_bf16 v[84:87], v[144:147], v[184:187], v[84:87]
	v_mfma_f32_16x16x32_bf16 v[76:79], v[152:155], v[184:187], v[76:79]
	s_setprio 0
	s_barrier
	s_add_i32 s42, 0, 0x14000
	s_add_i32 s39, s39, s23
	v_add_u32_e32 v139, s42, v137
	v_lshl_add_u64 v[202:203], s[16:17], 0, v[130:131]
	s_mov_b32 m0, s39
	ds_read_b128 v[190:193], v139
	ds_read_b128 v[194:197], v139 offset:1024
	ds_read_b128 v[198:201], v139 offset:2048
	ds_read_b128 v[216:219], v139 offset:3072
	global_load_lds_dwordx4 v[202:203], off
	v_lshl_add_u64 v[220:221], s[16:17], 0, v[128:129]
	s_add_i32 m0, s39, 0x2000
	s_nop 0
	global_load_lds_dwordx4 v[220:221], off
	s_barrier
	s_waitcnt lgkmcnt(0)
	s_setprio 1
	s_waitcnt lgkmcnt(0)
	v_mfma_f32_16x16x32_bf16 v[112:115], v[190:193], v[156:159], v[112:115]
	v_mfma_f32_16x16x32_bf16 v[104:107], v[198:201], v[156:159], v[104:107]
	v_mfma_f32_16x16x32_bf16 v[96:99], v[190:193], v[164:167], v[96:99]
	v_mfma_f32_16x16x32_bf16 v[88:91], v[198:201], v[164:167], v[88:91]
	v_mfma_f32_16x16x32_bf16 v[80:83], v[190:193], v[172:175], v[80:83]
	v_mfma_f32_16x16x32_bf16 v[72:75], v[198:201], v[172:175], v[72:75]
	v_mfma_f32_16x16x32_bf16 v[68:71], v[190:193], v[180:183], v[68:71]
	v_mfma_f32_16x16x32_bf16 v[64:67], v[198:201], v[180:183], v[64:67]
	v_mfma_f32_16x16x32_bf16 v[112:115], v[194:197], v[160:163], v[112:115]
	v_mfma_f32_16x16x32_bf16 v[104:107], v[216:219], v[160:163], v[104:107]
	v_mfma_f32_16x16x32_bf16 v[96:99], v[194:197], v[168:171], v[96:99]
	v_mfma_f32_16x16x32_bf16 v[88:91], v[216:219], v[168:171], v[88:91]
	v_mfma_f32_16x16x32_bf16 v[80:83], v[194:197], v[176:179], v[80:83]
	v_mfma_f32_16x16x32_bf16 v[72:75], v[216:219], v[176:179], v[72:75]
	v_mfma_f32_16x16x32_bf16 v[68:71], v[194:197], v[184:187], v[68:71]
	v_mfma_f32_16x16x32_bf16 v[64:67], v[216:219], v[184:187], v[64:67]
	s_setprio 0
	s_mov_b32 m0, s24
	v_lshl_add_u64 v[222:223], s[18:19], 0, v[130:131]
	s_barrier
	ds_read_b128 v[156:159], v138 offset:16384
	ds_read_b128 v[160:163], v138 offset:17408
	ds_read_b128 v[164:167], v138 offset:18432
	ds_read_b128 v[168:171], v138 offset:19456
	ds_read_b128 v[172:175], v138 offset:20480
	ds_read_b128 v[176:179], v138 offset:21504
	ds_read_b128 v[180:183], v138 offset:22528
	ds_read_b128 v[184:187], v138 offset:23552
	global_load_lds_dwordx4 v[222:223], off
	v_lshl_add_u64 v[224:225], s[18:19], 0, v[128:129]
	s_mov_b32 m0, s25
	s_nop 0
	global_load_lds_dwordx4 v[224:225], off
	s_barrier
	s_waitcnt lgkmcnt(0)
	s_setprio 1
	s_waitcnt lgkmcnt(0)
	v_mfma_f32_16x16x32_bf16 v[60:63], v[140:143], v[156:159], v[60:63]
	v_mfma_f32_16x16x32_bf16 v[56:59], v[148:151], v[156:159], v[56:59]
	v_mfma_f32_16x16x32_bf16 v[52:55], v[140:143], v[164:167], v[52:55]
	v_mfma_f32_16x16x32_bf16 v[44:47], v[148:151], v[164:167], v[44:47]
	v_mfma_f32_16x16x32_bf16 v[36:39], v[140:143], v[172:175], v[36:39]
	v_mfma_f32_16x16x32_bf16 v[28:31], v[148:151], v[172:175], v[28:31]
	v_mfma_f32_16x16x32_bf16 v[20:23], v[140:143], v[180:183], v[20:23]
	v_mfma_f32_16x16x32_bf16 v[12:15], v[148:151], v[180:183], v[12:15]
	v_mfma_f32_16x16x32_bf16 v[60:63], v[144:147], v[160:163], v[60:63]
	v_mfma_f32_16x16x32_bf16 v[56:59], v[152:155], v[160:163], v[56:59]
	v_mfma_f32_16x16x32_bf16 v[52:55], v[144:147], v[168:171], v[52:55]
	v_mfma_f32_16x16x32_bf16 v[44:47], v[152:155], v[168:171], v[44:47]
	v_mfma_f32_16x16x32_bf16 v[36:39], v[144:147], v[176:179], v[36:39]
	v_mfma_f32_16x16x32_bf16 v[28:31], v[152:155], v[176:179], v[28:31]
	v_mfma_f32_16x16x32_bf16 v[20:23], v[144:147], v[184:187], v[20:23]
	v_mfma_f32_16x16x32_bf16 v[12:15], v[152:155], v[184:187], v[12:15]
	s_setprio 0
	s_barrier
	s_add_u32 s40, s16, 0x40000
	s_addc_u32 s41, s17, 0
	s_add_i32 s39, s42, s23
	v_lshl_add_u64 v[140:141], s[40:41], 0, v[130:131]
	s_mov_b32 m0, s39
	s_nop 0
	global_load_lds_dwordx4 v[140:141], off
	v_lshl_add_u64 v[140:141], s[40:41], 0, v[128:129]
	s_add_i32 m0, s39, 0x2000
	s_nop 0
	global_load_lds_dwordx4 v[140:141], off
	s_waitcnt vmcnt(6)
	s_barrier
	s_setprio 1
	v_mfma_f32_16x16x32_bf16 v[48:51], v[190:193], v[156:159], v[48:51]
	v_mfma_f32_16x16x32_bf16 v[40:43], v[198:201], v[156:159], v[40:43]
	v_mfma_f32_16x16x32_bf16 v[32:35], v[190:193], v[164:167], v[32:35]
	v_mfma_f32_16x16x32_bf16 v[24:27], v[198:201], v[164:167], v[24:27]
	v_mfma_f32_16x16x32_bf16 v[16:19], v[190:193], v[172:175], v[16:19]
	v_mfma_f32_16x16x32_bf16 v[8:11], v[198:201], v[172:175], v[8:11]
	v_mfma_f32_16x16x32_bf16 v[4:7], v[190:193], v[180:183], v[4:7]
	v_mfma_f32_16x16x32_bf16 v[0:3], v[198:201], v[180:183], v[0:3]
	v_mfma_f32_16x16x32_bf16 v[48:51], v[194:197], v[160:163], v[48:51]
	v_mfma_f32_16x16x32_bf16 v[40:43], v[216:219], v[160:163], v[40:43]
	v_mfma_f32_16x16x32_bf16 v[32:35], v[194:197], v[168:171], v[32:35]
	v_mfma_f32_16x16x32_bf16 v[24:27], v[216:219], v[168:171], v[24:27]
	v_mfma_f32_16x16x32_bf16 v[16:19], v[194:197], v[176:179], v[16:19]
	v_mfma_f32_16x16x32_bf16 v[8:11], v[216:219], v[176:179], v[8:11]
	v_mfma_f32_16x16x32_bf16 v[4:7], v[194:197], v[184:187], v[4:7]
	v_mfma_f32_16x16x32_bf16 v[0:3], v[216:219], v[184:187], v[0:3]
	s_setprio 0
	s_add_i32 s39, 0, 0x18000
	v_add_u32_e32 v139, s39, v137
	s_barrier
	ds_read_b128 v[140:143], v139
	ds_read_b128 v[144:147], v139 offset:1024
	ds_read_b128 v[148:151], v139 offset:2048
	ds_read_b128 v[152:155], v139 offset:3072
	s_add_u32 s18, s18, 0x40000
	s_addc_u32 s19, s19, 0
	s_mov_b32 m0, s26
	v_lshl_add_u64 v[190:191], s[18:19], 0, v[130:131]
	ds_read_b128 v[156:159], v138 offset:32768
	ds_read_b128 v[160:163], v138 offset:33792
	ds_read_b128 v[164:167], v138 offset:34816
	ds_read_b128 v[168:171], v138 offset:35840
	ds_read_b128 v[172:175], v138 offset:36864
	ds_read_b128 v[176:179], v138 offset:37888
	ds_read_b128 v[180:183], v138 offset:38912
	ds_read_b128 v[184:187], v138 offset:39936
	global_load_lds_dwordx4 v[190:191], off
	v_lshl_add_u64 v[190:191], s[18:19], 0, v[128:129]
	s_mov_b32 m0, s27
	s_nop 0
	global_load_lds_dwordx4 v[190:191], off
	s_waitcnt lgkmcnt(8)
	s_barrier
	s_waitcnt lgkmcnt(0)
	s_setprio 1
	s_waitcnt lgkmcnt(0)
	v_mfma_f32_16x16x32_bf16 v[124:127], v[140:143], v[156:159], v[124:127]
	v_mfma_f32_16x16x32_bf16 v[120:123], v[148:151], v[156:159], v[120:123]
	v_mfma_f32_16x16x32_bf16 v[116:119], v[140:143], v[164:167], v[116:119]
	v_mfma_f32_16x16x32_bf16 v[108:111], v[148:151], v[164:167], v[108:111]
	v_mfma_f32_16x16x32_bf16 v[100:103], v[140:143], v[172:175], v[100:103]
	v_mfma_f32_16x16x32_bf16 v[92:95], v[148:151], v[172:175], v[92:95]
	v_mfma_f32_16x16x32_bf16 v[84:87], v[140:143], v[180:183], v[84:87]
	v_mfma_f32_16x16x32_bf16 v[76:79], v[148:151], v[180:183], v[76:79]
	v_mfma_f32_16x16x32_bf16 v[124:127], v[144:147], v[160:163], v[124:127]
	v_mfma_f32_16x16x32_bf16 v[120:123], v[152:155], v[160:163], v[120:123]
	v_mfma_f32_16x16x32_bf16 v[116:119], v[144:147], v[168:171], v[116:119]
	v_mfma_f32_16x16x32_bf16 v[108:111], v[152:155], v[168:171], v[108:111]
	v_mfma_f32_16x16x32_bf16 v[100:103], v[144:147], v[176:179], v[100:103]
	v_mfma_f32_16x16x32_bf16 v[92:95], v[152:155], v[176:179], v[92:95]
	v_mfma_f32_16x16x32_bf16 v[84:87], v[144:147], v[184:187], v[84:87]
	v_mfma_f32_16x16x32_bf16 v[76:79], v[152:155], v[184:187], v[76:79]
	s_setprio 0
	s_barrier
	s_add_i32 s18, 0, 0x1c000
	s_add_i32 s19, s39, s23
	v_add_u32_e32 v139, s18, v137
	v_lshl_add_u64 v[202:203], v[202:203], 0, s[92:93]
	s_mov_b32 m0, s19
	ds_read_b128 v[190:193], v139
	ds_read_b128 v[194:197], v139 offset:1024
	ds_read_b128 v[198:201], v139 offset:2048
	ds_read_b128 v[216:219], v139 offset:3072
	global_load_lds_dwordx4 v[202:203], off
	v_lshl_add_u64 v[202:203], v[220:221], 0, s[92:93]
	s_add_i32 m0, s19, 0x2000
	s_nop 0
	global_load_lds_dwordx4 v[202:203], off
	s_barrier
	s_waitcnt lgkmcnt(0)
	s_setprio 1
	s_waitcnt lgkmcnt(0)
	v_mfma_f32_16x16x32_bf16 v[112:115], v[190:193], v[156:159], v[112:115]
	v_mfma_f32_16x16x32_bf16 v[104:107], v[198:201], v[156:159], v[104:107]
	v_mfma_f32_16x16x32_bf16 v[96:99], v[190:193], v[164:167], v[96:99]
	v_mfma_f32_16x16x32_bf16 v[88:91], v[198:201], v[164:167], v[88:91]
	v_mfma_f32_16x16x32_bf16 v[80:83], v[190:193], v[172:175], v[80:83]
	v_mfma_f32_16x16x32_bf16 v[72:75], v[198:201], v[172:175], v[72:75]
	v_mfma_f32_16x16x32_bf16 v[68:71], v[190:193], v[180:183], v[68:71]
	v_mfma_f32_16x16x32_bf16 v[64:67], v[198:201], v[180:183], v[64:67]
	v_mfma_f32_16x16x32_bf16 v[112:115], v[194:197], v[160:163], v[112:115]
	v_mfma_f32_16x16x32_bf16 v[104:107], v[216:219], v[160:163], v[104:107]
	v_mfma_f32_16x16x32_bf16 v[96:99], v[194:197], v[168:171], v[96:99]
	v_mfma_f32_16x16x32_bf16 v[88:91], v[216:219], v[168:171], v[88:91]
	v_mfma_f32_16x16x32_bf16 v[80:83], v[194:197], v[176:179], v[80:83]
	v_mfma_f32_16x16x32_bf16 v[72:75], v[216:219], v[176:179], v[72:75]
	v_mfma_f32_16x16x32_bf16 v[68:71], v[194:197], v[184:187], v[68:71]
	v_mfma_f32_16x16x32_bf16 v[64:67], v[216:219], v[184:187], v[64:67]
	s_setprio 0
	s_mov_b32 m0, s28
	v_lshl_add_u64 v[202:203], v[222:223], 0, s[92:93]
	s_barrier
	ds_read_b128 v[156:159], v138 offset:49152
	ds_read_b128 v[160:163], v138 offset:50176
	ds_read_b128 v[164:167], v138 offset:51200
	ds_read_b128 v[168:171], v138 offset:52224
	ds_read_b128 v[172:175], v138 offset:53248
	ds_read_b128 v[176:179], v138 offset:54272
	ds_read_b128 v[180:183], v138 offset:55296
	ds_read_b128 v[184:187], v138 offset:56320
	global_load_lds_dwordx4 v[202:203], off
	v_lshl_add_u64 v[202:203], v[224:225], 0, s[92:93]
	s_mov_b32 m0, s29
	s_nop 0
	global_load_lds_dwordx4 v[202:203], off
	s_barrier
	s_waitcnt lgkmcnt(0)
	s_setprio 1
	s_waitcnt lgkmcnt(0)
	v_mfma_f32_16x16x32_bf16 v[60:63], v[140:143], v[156:159], v[60:63]
	v_mfma_f32_16x16x32_bf16 v[56:59], v[148:151], v[156:159], v[56:59]
	v_mfma_f32_16x16x32_bf16 v[52:55], v[140:143], v[164:167], v[52:55]
	v_mfma_f32_16x16x32_bf16 v[44:47], v[148:151], v[164:167], v[44:47]
	v_mfma_f32_16x16x32_bf16 v[36:39], v[140:143], v[172:175], v[36:39]
	v_mfma_f32_16x16x32_bf16 v[28:31], v[148:151], v[172:175], v[28:31]
	v_mfma_f32_16x16x32_bf16 v[20:23], v[140:143], v[180:183], v[20:23]
	v_mfma_f32_16x16x32_bf16 v[12:15], v[148:151], v[180:183], v[12:15]
	v_mfma_f32_16x16x32_bf16 v[60:63], v[144:147], v[160:163], v[60:63]
	v_mfma_f32_16x16x32_bf16 v[56:59], v[152:155], v[160:163], v[56:59]
	v_mfma_f32_16x16x32_bf16 v[52:55], v[144:147], v[168:171], v[52:55]
	v_mfma_f32_16x16x32_bf16 v[44:47], v[152:155], v[168:171], v[44:47]
	v_mfma_f32_16x16x32_bf16 v[36:39], v[144:147], v[176:179], v[36:39]
	v_mfma_f32_16x16x32_bf16 v[28:31], v[152:155], v[176:179], v[28:31]
	v_mfma_f32_16x16x32_bf16 v[20:23], v[144:147], v[184:187], v[20:23]
	v_mfma_f32_16x16x32_bf16 v[12:15], v[152:155], v[184:187], v[12:15]
	s_setprio 0
	s_barrier
	s_add_u32 s16, s16, 0x40080
	s_addc_u32 s17, s17, 0
	s_add_i32 s18, s18, s23
	v_lshl_add_u64 v[140:141], s[16:17], 0, v[130:131]
	s_mov_b32 m0, s18
	s_nop 0
	global_load_lds_dwordx4 v[140:141], off
	v_lshl_add_u64 v[140:141], s[16:17], 0, v[128:129]
	s_add_i32 m0, s18, 0x2000
	s_nop 0
	global_load_lds_dwordx4 v[140:141], off
	s_waitcnt vmcnt(6)
	s_barrier
	s_setprio 1
	v_mfma_f32_16x16x32_bf16 v[48:51], v[190:193], v[156:159], v[48:51]
	v_mfma_f32_16x16x32_bf16 v[40:43], v[198:201], v[156:159], v[40:43]
	v_mfma_f32_16x16x32_bf16 v[32:35], v[190:193], v[164:167], v[32:35]
	v_mfma_f32_16x16x32_bf16 v[24:27], v[198:201], v[164:167], v[24:27]
	v_mfma_f32_16x16x32_bf16 v[16:19], v[190:193], v[172:175], v[16:19]
	v_mfma_f32_16x16x32_bf16 v[8:11], v[198:201], v[172:175], v[8:11]
	v_mfma_f32_16x16x32_bf16 v[4:7], v[190:193], v[180:183], v[4:7]
	v_mfma_f32_16x16x32_bf16 v[0:3], v[198:201], v[180:183], v[0:3]
	v_mfma_f32_16x16x32_bf16 v[48:51], v[194:197], v[160:163], v[48:51]
	v_mfma_f32_16x16x32_bf16 v[40:43], v[216:219], v[160:163], v[40:43]
	v_mfma_f32_16x16x32_bf16 v[32:35], v[194:197], v[168:171], v[32:35]
	v_mfma_f32_16x16x32_bf16 v[24:27], v[216:219], v[168:171], v[24:27]
	v_mfma_f32_16x16x32_bf16 v[16:19], v[194:197], v[176:179], v[16:19]
	v_mfma_f32_16x16x32_bf16 v[8:11], v[216:219], v[176:179], v[8:11]
	v_mfma_f32_16x16x32_bf16 v[4:7], v[194:197], v[184:187], v[4:7]
	v_mfma_f32_16x16x32_bf16 v[0:3], v[216:219], v[184:187], v[0:3]
	s_setprio 0
	s_add_i32 s38, s38, 2
	s_add_u32 s14, s14, 0x100
	s_addc_u32 s15, s15, 0
	s_add_u32 s36, s36, 0x100
	s_addc_u32 s37, s37, 0
	s_cmp_gt_u32 s38, 13
	s_barrier
	s_cbranch_scc0 .LBB0_150
	v_lshl_add_u32 v140, s33, 8, v136
	s_lshl_b32 s14, s31, 8
	v_ashrrev_i32_e32 v141, 31, v140
	v_readlane_b32 s16, v252, 62
	s_ashr_i32 s15, s14, 31
	v_lshlrev_b64 v[142:143], 11, v[140:141]
	v_readlane_b32 s17, v252, 63
	s_lshl_b64 s[14:15], s[14:15], 1
	v_cvt_pk_bf16_f32 v104, v104, v105
	v_lshl_add_u64 v[142:143], s[16:17], 0, v[142:143]
	v_lshl_add_u64 v[142:143], v[142:143], 0, s[14:15]
	v_lshl_add_u64 v[142:143], v[142:143], 0, s[0:1]
	v_lshl_add_u64 v[142:143], v[142:143], 0, v[188:189]
	v_cvt_pk_bf16_f32 v105, v106, v107
	v_and_b32_e32 v230, 16, v204
	v_lshrrev_b32_e32 v231, 1, v230
	v_add_u32_e32 v230, v230, v231
	v_mov_b32_e32 v231, v189
	v_mov_b64_e32 v[234:235], v[104:105]
	v_or_b32_e32 v104, 16, v140
	v_ashrrev_i32_e32 v105, 31, v104
	v_lshlrev_b64 v[104:105], 11, v[104:105]
	v_lshl_add_u64 v[104:105], s[16:17], 0, v[104:105]
	v_lshl_add_u64 v[104:105], v[104:105], 0, s[14:15]
	v_lshl_add_u64 v[104:105], v[104:105], 0, s[0:1]
	v_lshl_add_u64 v[104:105], v[104:105], 0, v[188:189]
	v_cvt_pk_bf16_f32 v88, v88, v89
	v_cvt_pk_bf16_f32 v89, v90, v91
	v_mov_b64_e32 v[238:239], v[88:89]
	v_or_b32_e32 v88, 32, v140
	v_ashrrev_i32_e32 v89, 31, v88
	v_lshlrev_b64 v[88:89], 11, v[88:89]
	v_lshl_add_u64 v[88:89], s[16:17], 0, v[88:89]
	v_lshl_add_u64 v[88:89], v[88:89], 0, s[14:15]
	v_lshl_add_u64 v[88:89], v[88:89], 0, s[0:1]
	v_lshl_add_u64 v[88:89], v[88:89], 0, v[188:189]
	v_cvt_pk_bf16_f32 v72, v72, v73
	v_cvt_pk_bf16_f32 v73, v74, v75
	v_mov_b64_e32 v[242:243], v[72:73]
	v_or_b32_e32 v72, 48, v140
	v_ashrrev_i32_e32 v73, 31, v72
	v_lshlrev_b64 v[72:73], 11, v[72:73]
	v_lshl_add_u64 v[72:73], s[16:17], 0, v[72:73]
	v_lshl_add_u64 v[72:73], v[72:73], 0, s[14:15]
	v_lshl_add_u64 v[72:73], v[72:73], 0, s[0:1]
	v_lshl_add_u64 v[72:73], v[72:73], 0, v[188:189]
	v_cvt_pk_bf16_f32 v64, v64, v65
	v_cvt_pk_bf16_f32 v65, v66, v67
	v_mov_b64_e32 v[246:247], v[64:65]
	v_add_u32_e32 v64, 0x80, v140
	v_ashrrev_i32_e32 v65, 31, v64
	v_lshlrev_b64 v[64:65], 11, v[64:65]
	v_lshl_add_u64 v[64:65], s[16:17], 0, v[64:65]
	v_lshl_add_u64 v[64:65], v[64:65], 0, s[14:15]
	v_lshl_add_u64 v[64:65], v[64:65], 0, s[0:1]
	v_lshl_add_u64 v[64:65], v[64:65], 0, v[188:189]
	v_cvt_pk_bf16_f32 v40, v40, v41
	v_cvt_pk_bf16_f32 v41, v42, v43
	v_mov_b64_e32 v[150:151], v[40:41]
	v_add_u32_e32 v40, 0x90, v140
	v_ashrrev_i32_e32 v41, 31, v40
	v_lshlrev_b64 v[40:41], 11, v[40:41]
	v_lshl_add_u64 v[40:41], s[16:17], 0, v[40:41]
	v_lshl_add_u64 v[40:41], v[40:41], 0, s[14:15]
	v_lshl_add_u64 v[40:41], v[40:41], 0, s[0:1]
	v_lshl_add_u64 v[40:41], v[40:41], 0, v[188:189]
	v_cvt_pk_bf16_f32 v24, v24, v25
	v_cvt_pk_bf16_f32 v25, v26, v27
	v_mov_b64_e32 v[154:155], v[24:25]
	v_add_u32_e32 v24, 0xa0, v140
	v_ashrrev_i32_e32 v25, 31, v24
	v_lshlrev_b64 v[24:25], 11, v[24:25]
	v_lshl_add_u64 v[24:25], s[16:17], 0, v[24:25]
	v_lshl_add_u64 v[24:25], v[24:25], 0, s[14:15]
	v_lshl_add_u64 v[24:25], v[24:25], 0, s[0:1]
	v_lshl_add_u64 v[24:25], v[24:25], 0, v[188:189]
	v_cvt_pk_bf16_f32 v8, v8, v9
	v_cvt_pk_bf16_f32 v9, v10, v11
	v_mov_b64_e32 v[158:159], v[8:9]
	v_add_u32_e32 v8, 0xb0, v140
	v_ashrrev_i32_e32 v9, 31, v8
	v_lshlrev_b64 v[8:9], 11, v[8:9]
	v_lshl_add_u64 v[8:9], s[16:17], 0, v[8:9]
	v_lshl_add_u64 v[8:9], v[8:9], 0, s[14:15]
	v_lshl_add_u64 v[8:9], v[8:9], 0, s[0:1]
	v_cvt_pk_bf16_f32 v106, v116, v117
	v_cvt_pk_bf16_f32 v107, v118, v119
	v_cvt_pk_bf16_f32 v90, v100, v101
	v_cvt_pk_bf16_f32 v91, v102, v103
	v_cvt_pk_bf16_f32 v74, v84, v85
	v_cvt_pk_bf16_f32 v75, v86, v87
	v_cvt_pk_bf16_f32 v42, v52, v53
	v_cvt_pk_bf16_f32 v43, v54, v55
	v_cvt_pk_bf16_f32 v26, v36, v37
	v_cvt_pk_bf16_f32 v27, v38, v39
	v_lshl_add_u64 v[8:9], v[8:9], 0, v[188:189]
	v_cvt_pk_bf16_f32 v10, v20, v21
	v_cvt_pk_bf16_f32 v11, v22, v23
	v_cvt_pk_bf16_f32 v124, v124, v125
	v_cvt_pk_bf16_f32 v125, v126, v127
	v_cvt_pk_bf16_f32 v120, v120, v121
	v_cvt_pk_bf16_f32 v121, v122, v123
	v_cvt_pk_bf16_f32 v112, v112, v113
	v_cvt_pk_bf16_f32 v113, v114, v115
	v_mov_b64_e32 v[160:161], v[106:107]
	v_cvt_pk_bf16_f32 v106, v108, v109
	v_cvt_pk_bf16_f32 v107, v110, v111
	v_cvt_pk_bf16_f32 v96, v96, v97
	v_cvt_pk_bf16_f32 v97, v98, v99
	v_mov_b64_e32 v[164:165], v[90:91]
	v_cvt_pk_bf16_f32 v90, v92, v93
	v_cvt_pk_bf16_f32 v91, v94, v95
	v_cvt_pk_bf16_f32 v80, v80, v81
	v_cvt_pk_bf16_f32 v81, v82, v83
	v_mov_b64_e32 v[168:169], v[74:75]
	v_cvt_pk_bf16_f32 v74, v76, v77
	v_cvt_pk_bf16_f32 v75, v78, v79
	v_cvt_pk_bf16_f32 v68, v68, v69
	v_cvt_pk_bf16_f32 v69, v70, v71
	v_cvt_pk_bf16_f32 v60, v60, v61
	v_cvt_pk_bf16_f32 v61, v62, v63
	v_cvt_pk_bf16_f32 v56, v56, v57
	v_cvt_pk_bf16_f32 v57, v58, v59
	v_cvt_pk_bf16_f32 v48, v48, v49
	v_cvt_pk_bf16_f32 v49, v50, v51
	v_mov_b64_e32 v[172:173], v[42:43]
	v_cvt_pk_bf16_f32 v42, v44, v45
	v_cvt_pk_bf16_f32 v43, v46, v47
	v_cvt_pk_bf16_f32 v32, v32, v33
	v_cvt_pk_bf16_f32 v33, v34, v35
	v_mov_b64_e32 v[176:177], v[26:27]
	v_cvt_pk_bf16_f32 v26, v28, v29
	v_cvt_pk_bf16_f32 v27, v30, v31
	v_cvt_pk_bf16_f32 v16, v16, v17
	v_cvt_pk_bf16_f32 v17, v18, v19
	v_mov_b64_e32 v[180:181], v[10:11]
	v_cvt_pk_bf16_f32 v10, v12, v13
	v_cvt_pk_bf16_f32 v11, v14, v15
	v_cvt_pk_bf16_f32 v4, v4, v5
	v_cvt_pk_bf16_f32 v5, v6, v7
	v_cvt_pk_bf16_f32 v0, v0, v1
	v_cvt_pk_bf16_f32 v1, v2, v3
	s_and_b64 vcc, exec, s[8:9]
	s_mov_b32 s31, s4
	s_mov_b32 s33, s2
	s_mov_b64 s[16:17], s[12:13]
	s_mov_b64 s[14:15], s[10:11]
	global_store_dwordx2 v[142:143], v[124:125], off
	global_store_dwordx2 v[142:143], v[120:121], off offset:32
	v_mov_b64_e32 v[232:233], v[112:113]
	s_nop 1
	v_permlane16_swap_b32 v232, v234
	v_permlane16_swap_b32 v233, v235
	v_lshl_add_u64 v[248:249], v[142:143], 0, v[230:231]
	global_store_dwordx4 v[248:249], v[232:235], off offset:256
	s_nop 1
	v_mov_b64_e32 v[162:163], v[106:107]
	s_nop 1
	v_permlane16_swap_b32 v160, v162
	v_permlane16_swap_b32 v161, v163
	v_lshl_add_u64 v[248:249], v[104:105], 0, v[230:231]
	global_store_dwordx4 v[248:249], v[160:163], off
	s_nop 1
	v_mov_b64_e32 v[236:237], v[96:97]
	s_nop 1
	v_permlane16_swap_b32 v236, v238
	v_permlane16_swap_b32 v237, v239
	v_lshl_add_u64 v[248:249], v[104:105], 0, v[230:231]
	global_store_dwordx4 v[248:249], v[236:239], off offset:256
	s_nop 1
	v_mov_b64_e32 v[166:167], v[90:91]
	s_nop 1
	v_permlane16_swap_b32 v164, v166
	v_permlane16_swap_b32 v165, v167
	v_lshl_add_u64 v[248:249], v[88:89], 0, v[230:231]
	global_store_dwordx4 v[248:249], v[164:167], off
	s_nop 1
	v_mov_b64_e32 v[240:241], v[80:81]
	s_nop 1
	v_permlane16_swap_b32 v240, v242
	v_permlane16_swap_b32 v241, v243
	v_lshl_add_u64 v[248:249], v[88:89], 0, v[230:231]
	global_store_dwordx4 v[248:249], v[240:243], off offset:256
	s_nop 1
	v_mov_b64_e32 v[170:171], v[74:75]
	s_nop 1
	v_permlane16_swap_b32 v168, v170
	v_permlane16_swap_b32 v169, v171
	v_lshl_add_u64 v[248:249], v[72:73], 0, v[230:231]
	global_store_dwordx4 v[248:249], v[168:171], off
	s_nop 1
	v_mov_b64_e32 v[244:245], v[68:69]
	s_nop 1
	v_permlane16_swap_b32 v244, v246
	v_permlane16_swap_b32 v245, v247
	v_lshl_add_u64 v[248:249], v[72:73], 0, v[230:231]
	global_store_dwordx4 v[248:249], v[244:247], off offset:256
	s_nop 1
	v_mov_b64_e32 v[232:233], v[60:61]
	v_mov_b64_e32 v[234:235], v[56:57]
	s_nop 1
	v_permlane16_swap_b32 v232, v234
	v_permlane16_swap_b32 v233, v235
	v_lshl_add_u64 v[248:249], v[64:65], 0, v[230:231]
	global_store_dwordx4 v[248:249], v[232:235], off
	s_nop 1
	v_mov_b64_e32 v[148:149], v[48:49]
	s_nop 1
	v_permlane16_swap_b32 v148, v150
	v_permlane16_swap_b32 v149, v151
	v_lshl_add_u64 v[248:249], v[64:65], 0, v[230:231]
	global_store_dwordx4 v[248:249], v[148:151], off offset:256
	s_nop 1
	v_mov_b64_e32 v[174:175], v[42:43]
	s_nop 1
	v_permlane16_swap_b32 v172, v174
	v_permlane16_swap_b32 v173, v175
	v_lshl_add_u64 v[248:249], v[40:41], 0, v[230:231]
	global_store_dwordx4 v[248:249], v[172:175], off
	s_nop 1
	v_mov_b64_e32 v[152:153], v[32:33]
	s_nop 1
	v_permlane16_swap_b32 v152, v154
	v_permlane16_swap_b32 v153, v155
	v_lshl_add_u64 v[248:249], v[40:41], 0, v[230:231]
	global_store_dwordx4 v[248:249], v[152:155], off offset:256
	s_nop 1
	v_mov_b64_e32 v[178:179], v[26:27]
	s_nop 1
	v_permlane16_swap_b32 v176, v178
	v_permlane16_swap_b32 v177, v179
	v_lshl_add_u64 v[248:249], v[24:25], 0, v[230:231]
	global_store_dwordx4 v[248:249], v[176:179], off
	s_nop 1
	v_mov_b64_e32 v[156:157], v[16:17]
	s_nop 1
	v_permlane16_swap_b32 v156, v158
	v_permlane16_swap_b32 v157, v159
	v_lshl_add_u64 v[248:249], v[24:25], 0, v[230:231]
	global_store_dwordx4 v[248:249], v[156:159], off offset:256
	s_nop 1
	v_mov_b64_e32 v[182:183], v[10:11]
	s_nop 1
	v_permlane16_swap_b32 v180, v182
	v_permlane16_swap_b32 v181, v183
	v_lshl_add_u64 v[248:249], v[8:9], 0, v[230:231]
	global_store_dwordx4 v[248:249], v[180:183], off
	s_nop 1
	v_mov_b64_e32 v[232:233], v[4:5]
	v_mov_b64_e32 v[234:235], v[0:1]
	s_nop 1
	v_permlane16_swap_b32 v232, v234
	v_permlane16_swap_b32 v233, v235
	v_lshl_add_u64 v[248:249], v[8:9], 0, v[230:231]
	global_store_dwordx4 v[248:249], v[232:235], off offset:256
	s_nop 1
	s_cbranch_vccz .LBB0_147
	s_waitcnt vmcnt(0)
	s_cmpk_gt_u32 s20, 0xff
	s_mov_b32 s28, 0x8000
	s_movk_i32 s29, 0xc0
	s_mov_b32 s30, 0x800000
	s_movk_i32 s31, 0x7fff
	s_movk_i32 s33, 0x1800
	s_cbranch_scc1 .LBB0_154
	s_barrier

.LBB0_310:
	s_and_b64 vcc, exec, s[4:5]
	s_cbranch_vccz .LBB0_263
	v_mov_b32_e32 v14, v204
	v_mov_b64_e32 v[6:7], s[88:89]
	v_readfirstlane_b32 s5, v14
	s_ashr_i32 s4, s5, 6
	s_and_b32 s13, s4, 1
	v_bfe_u32 v0, v14, 3, 3
	v_lshl_or_b32 v8, s4, 3, v0
	v_and_b32_e32 v0, 7, v14
	s_lshl_b32 s2, s13, 2
	v_bfe_u32 v15, v14, 4, 2
	v_bitop3_b32 v2, s2, v0, v15 bitop3:0x36
	v_add_u32_e32 v9, s11, v8
	v_mad_i64_i32 v[0:1], s[2:3], v9, s84, v[6:7]
	v_lshlrev_b32_e32 v188, 4, v2
	v_add_u32_e32 v2, 64, v9
	v_add_u32_e32 v4, 0x80, v9
	v_add_u32_e32 v9, 0xc0, v9
	v_mad_i64_i32 v[2:3], s[2:3], v2, s84, v[6:7]
	v_mad_i64_i32 v[4:5], s[2:3], v4, s84, v[6:7]
	v_mad_i64_i32 v[6:7], s[2:3], v9, s84, v[6:7]
	v_add_u32_e32 v12, s0, v8
	v_mov_b64_e32 v[8:9], s[8:9]
	v_mad_i64_i32 v[10:11], s[2:3], v12, s77, v[8:9]
	v_add_u32_e32 v12, 64, v12
	v_mad_i64_i32 v[8:9], s[2:3], v12, s77, v[8:9]
	s_lshl_b32 s2, s4, 10
	s_add_i32 s26, s2, 0
	v_lshl_add_u64 v[0:1], v[0:1], 0, v[188:189]
	s_mov_b32 m0, s26
	s_add_i32 s21, s26, 0x2000
	v_lshl_add_u64 v[2:3], v[2:3], 0, v[188:189]
	global_load_lds_dwordx4 v[0:1], off
	s_mov_b32 m0, s21
	s_add_i32 s22, s26, 0x4000
	v_lshl_add_u64 v[4:5], v[4:5], 0, v[188:189]
	global_load_lds_dwordx4 v[2:3], off
	s_mov_b32 m0, s22
	s_add_i32 s23, s26, 0x6000
	v_lshl_add_u64 v[6:7], v[6:7], 0, v[188:189]
	global_load_lds_dwordx4 v[4:5], off
	s_mov_b32 m0, s23
	s_add_i32 s24, s26, 0x8000
	v_lshl_add_u64 v[10:11], v[10:11], 0, v[188:189]
	global_load_lds_dwordx4 v[6:7], off
	s_mov_b32 m0, s24
	s_add_i32 s25, s26, 0xa000
	v_lshl_add_u64 v[8:9], v[8:9], 0, v[188:189]
	global_load_lds_dwordx4 v[10:11], off
	s_mov_b32 m0, s25
	s_add_i32 s18, s26, 0xc000
	global_load_lds_dwordx4 v[8:9], off
	v_lshl_add_u64 v[12:13], v[0:1], 0, s[92:93]
	s_mov_b32 m0, s18
	s_add_i32 s2, s26, 0xe000
	global_load_lds_dwordx4 v[12:13], off
	v_lshl_add_u64 v[12:13], v[2:3], 0, s[92:93]
	s_mov_b32 m0, s2
	s_add_i32 s4, s26, 0x10000
	global_load_lds_dwordx4 v[12:13], off
	v_lshl_add_u64 v[12:13], v[4:5], 0, s[92:93]
	s_mov_b32 m0, s4
	s_add_i32 s12, s26, 0x12000
	global_load_lds_dwordx4 v[12:13], off
	v_lshl_add_u64 v[12:13], v[6:7], 0, s[92:93]
	s_mov_b32 m0, s12
	s_add_i32 s14, s26, 0x14000
	global_load_lds_dwordx4 v[12:13], off
	v_lshl_add_u64 v[12:13], v[10:11], 0, s[92:93]
	s_mov_b32 m0, s14
	s_add_i32 s16, s26, 0x16000
	global_load_lds_dwordx4 v[12:13], off
	v_lshl_add_u64 v[12:13], v[8:9], 0, s[92:93]
	s_mov_b32 m0, s16
	s_lshr_b32 s3, s5, 1
	global_load_lds_dwordx4 v[12:13], off
	v_bfe_u32 v13, v14, 1, 3
	v_and_b32_e32 v12, 15, v14
	v_xor_b32_e32 v13, v15, v13
	s_and_b32 s3, s3, 0x1ffffc0
	s_waitcnt vmcnt(6)
	v_lshlrev_b32_e32 v140, 4, v13
	v_or_b32_e32 v13, s3, v12
	s_mov_b64 s[34:35], 0x100
	s_add_i32 s19, s26, 0x18000
	s_waitcnt lgkmcnt(0)
	s_barrier
	v_lshlrev_b32_e32 v141, 7, v13
	v_lshlrev_b32_e32 v142, 7, v12
	v_lshl_add_u64 v[12:13], v[0:1], 0, s[34:35]
	s_mov_b32 m0, s19
	s_add_i32 s3, s26, 0x1a000
	global_load_lds_dwordx4 v[12:13], off
	v_lshl_add_u64 v[12:13], v[2:3], 0, s[34:35]
	s_mov_b32 m0, s3
	s_add_i32 s5, s26, 0x1c000
	s_lshl_b32 s20, s13, 13
	global_load_lds_dwordx4 v[12:13], off
	v_lshl_add_u64 v[12:13], v[4:5], 0, s[34:35]
	s_mov_b32 m0, s5
	s_add_i32 s13, s26, 0x1e000
	global_load_lds_dwordx4 v[12:13], off
	v_lshl_add_u64 v[12:13], v[6:7], 0, s[34:35]
	s_mov_b32 m0, s13
	s_add_i32 s15, s26, 0x20000
	global_load_lds_dwordx4 v[12:13], off
	v_lshl_add_u64 v[12:13], v[10:11], 0, s[34:35]
	s_mov_b32 m0, s15
	s_add_i32 s17, s26, 0x22000
	global_load_lds_dwordx4 v[12:13], off
	v_lshl_add_u64 v[12:13], v[8:9], 0, s[34:35]
	s_mov_b32 m0, s17
	v_xor_b32_e32 v143, 64, v140
	global_load_lds_dwordx4 v[12:13], off
	s_add_i32 s27, s20, 0
	v_add_u32_e32 v44, 0, v141
	v_add_u32_e32 v112, s27, v142
	v_add_u32_e32 v144, v44, v140
	v_add_u32_e32 v145, v112, v140
	v_add_u32_e32 v147, v44, v143
	ds_read_b128 v[12:15], v144
	s_waitcnt lgkmcnt(0)
	ds_read_b128 v[16:19], v144 offset:2048
	ds_read_b128 v[20:23], v144 offset:4096
	ds_read_b128 v[24:27], v144 offset:6144
	ds_read_b128 v[28:31], v145 offset:32768
	ds_read_b128 v[32:35], v145 offset:34816
	ds_read_b128 v[36:39], v145 offset:36864
	ds_read_b128 v[40:43], v145 offset:38912
	v_add_u32_e32 v146, v112, v143
	ds_read_b128 v[44:47], v147
	ds_read_b128 v[48:51], v147 offset:2048
	ds_read_b128 v[52:55], v147 offset:4096
	ds_read_b128 v[56:59], v147 offset:6144
	ds_read_b128 v[60:63], v146 offset:32768
	ds_read_b128 v[64:67], v146 offset:34816
	ds_read_b128 v[68:71], v146 offset:36864
	ds_read_b128 v[72:75], v146 offset:38912
	s_waitcnt lgkmcnt(0)
	v_mfma_f32_16x16x32_bf16 v[76:79], v[28:31], v[12:15], 0
	v_mfma_f32_16x16x32_bf16 v[80:83], v[32:35], v[12:15], 0
	v_mfma_f32_16x16x32_bf16 v[84:87], v[36:39], v[12:15], 0
	v_mfma_f32_16x16x32_bf16 v[12:15], v[40:43], v[12:15], 0
	v_mfma_f32_16x16x32_bf16 v[88:91], v[28:31], v[16:19], 0
	v_mfma_f32_16x16x32_bf16 v[92:95], v[32:35], v[16:19], 0
	v_mfma_f32_16x16x32_bf16 v[96:99], v[36:39], v[16:19], 0
	v_mfma_f32_16x16x32_bf16 v[16:19], v[40:43], v[16:19], 0
	v_mfma_f32_16x16x32_bf16 v[100:103], v[28:31], v[20:23], 0
	v_mfma_f32_16x16x32_bf16 v[104:107], v[32:35], v[20:23], 0
	v_mfma_f32_16x16x32_bf16 v[108:111], v[36:39], v[20:23], 0
	v_mfma_f32_16x16x32_bf16 v[20:23], v[40:43], v[20:23], 0
	v_mfma_f32_16x16x32_bf16 v[28:31], v[28:31], v[24:27], 0
	v_mfma_f32_16x16x32_bf16 v[32:35], v[32:35], v[24:27], 0
	v_mfma_f32_16x16x32_bf16 v[36:39], v[36:39], v[24:27], 0
	v_mfma_f32_16x16x32_bf16 v[24:27], v[40:43], v[24:27], 0
	v_mfma_f32_16x16x32_bf16 v[40:43], v[60:63], v[44:47], v[76:79]
	v_mfma_f32_16x16x32_bf16 v[76:79], v[64:67], v[44:47], v[80:83]
	v_mfma_f32_16x16x32_bf16 v[80:83], v[68:71], v[44:47], v[84:87]
	v_mfma_f32_16x16x32_bf16 v[12:15], v[72:75], v[44:47], v[12:15]
	v_mfma_f32_16x16x32_bf16 v[44:47], v[60:63], v[48:51], v[88:91]
	v_mfma_f32_16x16x32_bf16 v[84:87], v[64:67], v[48:51], v[92:95]
	v_mfma_f32_16x16x32_bf16 v[88:91], v[68:71], v[48:51], v[96:99]
	v_mfma_f32_16x16x32_bf16 v[16:19], v[72:75], v[48:51], v[16:19]
	v_mfma_f32_16x16x32_bf16 v[48:51], v[60:63], v[52:55], v[100:103]
	v_mfma_f32_16x16x32_bf16 v[92:95], v[64:67], v[52:55], v[104:107]
	v_mfma_f32_16x16x32_bf16 v[96:99], v[68:71], v[52:55], v[108:111]
	v_mfma_f32_16x16x32_bf16 v[20:23], v[72:75], v[52:55], v[20:23]
	v_mfma_f32_16x16x32_bf16 v[28:31], v[60:63], v[56:59], v[28:31]
	v_mfma_f32_16x16x32_bf16 v[32:35], v[64:67], v[56:59], v[32:35]
	v_mfma_f32_16x16x32_bf16 v[36:39], v[68:71], v[56:59], v[36:39]
	v_mfma_f32_16x16x32_bf16 v[24:27], v[72:75], v[56:59], v[24:27]
	s_mov_b32 m0, s26
	s_waitcnt vmcnt(6)
	s_mov_b64 s[26:27], 0x180
	s_waitcnt lgkmcnt(0)
	s_barrier
	v_lshl_add_u64 v[52:53], v[0:1], 0, s[26:27]
	global_load_lds_dwordx4 v[52:53], off
	v_lshl_add_u64 v[52:53], v[2:3], 0, s[26:27]
	s_mov_b32 m0, s21
	s_nop 0
	global_load_lds_dwordx4 v[52:53], off
	v_lshl_add_u64 v[52:53], v[4:5], 0, s[26:27]
	s_mov_b32 m0, s22
	s_nop 0
	global_load_lds_dwordx4 v[52:53], off
	v_lshl_add_u64 v[52:53], v[6:7], 0, s[26:27]
	s_mov_b32 m0, s23
	s_nop 0
	global_load_lds_dwordx4 v[52:53], off
	v_lshl_add_u64 v[52:53], v[10:11], 0, s[26:27]
	s_mov_b32 m0, s24
	s_nop 0
	global_load_lds_dwordx4 v[52:53], off
	v_lshl_add_u64 v[52:53], v[8:9], 0, s[26:27]
	s_mov_b32 m0, s25
	s_nop 0
	global_load_lds_dwordx4 v[52:53], off
	v_add_u32_e32 v108, 0xc000, v112
	v_add_u32_e32 v148, v108, v140
	ds_read_b128 v[52:55], v144 offset:49152
	ds_read_b128 v[56:59], v144 offset:51200
	ds_read_b128 v[60:63], v144 offset:53248
	ds_read_b128 v[64:67], v144 offset:55296
	ds_read_b128 v[68:71], v148 offset:32768
	ds_read_b128 v[72:75], v148 offset:34816
	ds_read_b128 v[100:103], v148 offset:36864
	ds_read_b128 v[104:107], v148 offset:38912
	v_add_u32_e32 v149, v108, v143
	ds_read_b128 v[108:111], v147 offset:49152
	ds_read_b128 v[112:115], v147 offset:51200
	ds_read_b128 v[116:119], v147 offset:53248
	ds_read_b128 v[120:123], v147 offset:55296
	ds_read_b128 v[124:127], v149 offset:32768
	ds_read_b128 v[128:131], v149 offset:34816
	ds_read_b128 v[132:135], v149 offset:36864
	ds_read_b128 v[136:139], v149 offset:38912
	s_waitcnt lgkmcnt(0)
	v_mfma_f32_16x16x32_bf16 v[40:43], v[68:71], v[52:55], v[40:43]
	v_mfma_f32_16x16x32_bf16 v[76:79], v[72:75], v[52:55], v[76:79]
	v_mfma_f32_16x16x32_bf16 v[80:83], v[100:103], v[52:55], v[80:83]
	v_mfma_f32_16x16x32_bf16 v[12:15], v[104:107], v[52:55], v[12:15]
	v_mfma_f32_16x16x32_bf16 v[44:47], v[68:71], v[56:59], v[44:47]
	v_mfma_f32_16x16x32_bf16 v[52:55], v[72:75], v[56:59], v[84:87]
	v_mfma_f32_16x16x32_bf16 v[84:87], v[100:103], v[56:59], v[88:91]
	v_mfma_f32_16x16x32_bf16 v[16:19], v[104:107], v[56:59], v[16:19]
	v_mfma_f32_16x16x32_bf16 v[48:51], v[68:71], v[60:63], v[48:51]
	v_mfma_f32_16x16x32_bf16 v[56:59], v[72:75], v[60:63], v[92:95]
	v_mfma_f32_16x16x32_bf16 v[88:91], v[100:103], v[60:63], v[96:99]
	v_mfma_f32_16x16x32_bf16 v[20:23], v[104:107], v[60:63], v[20:23]
	v_mfma_f32_16x16x32_bf16 v[28:31], v[68:71], v[64:67], v[28:31]
	v_mfma_f32_16x16x32_bf16 v[32:35], v[72:75], v[64:67], v[32:35]
	v_mfma_f32_16x16x32_bf16 v[36:39], v[100:103], v[64:67], v[36:39]
	v_mfma_f32_16x16x32_bf16 v[24:27], v[104:107], v[64:67], v[24:27]
	v_mfma_f32_16x16x32_bf16 v[40:43], v[124:127], v[108:111], v[40:43]
	v_mfma_f32_16x16x32_bf16 v[60:63], v[128:131], v[108:111], v[76:79]
	v_mfma_f32_16x16x32_bf16 v[64:67], v[132:135], v[108:111], v[80:83]
	v_mfma_f32_16x16x32_bf16 v[12:15], v[136:139], v[108:111], v[12:15]
	v_mfma_f32_16x16x32_bf16 v[44:47], v[124:127], v[112:115], v[44:47]
	v_mfma_f32_16x16x32_bf16 v[52:55], v[128:131], v[112:115], v[52:55]
	v_mfma_f32_16x16x32_bf16 v[68:71], v[132:135], v[112:115], v[84:87]
	v_mfma_f32_16x16x32_bf16 v[16:19], v[136:139], v[112:115], v[16:19]
	v_mfma_f32_16x16x32_bf16 v[48:51], v[124:127], v[116:119], v[48:51]
	v_mfma_f32_16x16x32_bf16 v[56:59], v[128:131], v[116:119], v[56:59]
	v_mfma_f32_16x16x32_bf16 v[72:75], v[132:135], v[116:119], v[88:91]
	v_mfma_f32_16x16x32_bf16 v[20:23], v[136:139], v[116:119], v[20:23]
	v_mfma_f32_16x16x32_bf16 v[28:31], v[124:127], v[120:123], v[28:31]
	v_mfma_f32_16x16x32_bf16 v[32:35], v[128:131], v[120:123], v[32:35]
	v_mfma_f32_16x16x32_bf16 v[36:39], v[132:135], v[120:123], v[36:39]
	v_mfma_f32_16x16x32_bf16 v[24:27], v[136:139], v[120:123], v[24:27]
	s_waitcnt vmcnt(6)
	s_mov_b64 s[22:23], 0x200
	s_mov_b32 m0, s18
	s_waitcnt lgkmcnt(0)
	s_barrier
	v_lshl_add_u64 v[76:77], v[0:1], 0, s[22:23]
	global_load_lds_dwordx4 v[76:77], off
	v_lshl_add_u64 v[76:77], v[2:3], 0, s[22:23]
	s_mov_b32 m0, s2
	s_nop 0
	global_load_lds_dwordx4 v[76:77], off
	v_lshl_add_u64 v[76:77], v[4:5], 0, s[22:23]
	s_mov_b32 m0, s4
	s_nop 0
	global_load_lds_dwordx4 v[76:77], off
	v_lshl_add_u64 v[76:77], v[6:7], 0, s[22:23]
	s_mov_b32 m0, s12
	s_nop 0
	global_load_lds_dwordx4 v[76:77], off
	v_lshl_add_u64 v[76:77], v[10:11], 0, s[22:23]
	s_mov_b32 m0, s14
	s_nop 0
	global_load_lds_dwordx4 v[76:77], off
	v_lshl_add_u64 v[76:77], v[8:9], 0, s[22:23]
	s_mov_b32 m0, s16
	s_nop 0
	global_load_lds_dwordx4 v[76:77], off
	s_add_i32 s2, 0, 0x18000
	v_add_u32_e32 v108, s2, v141
	s_add_i32 s2, s2, s20
	v_add_u32_e32 v109, s2, v142
	v_add_u32_e32 v141, v108, v140
	v_add_u32_e32 v140, v109, v140
	v_add_u32_e32 v142, v109, v143
	v_add_u32_e32 v143, v108, v143
	ds_read_b128 v[76:79], v141
	ds_read_b128 v[80:83], v141 offset:2048
	ds_read_b128 v[84:87], v141 offset:4096
	ds_read_b128 v[88:91], v141 offset:6144
	ds_read_b128 v[92:95], v140 offset:32768
	ds_read_b128 v[96:99], v140 offset:34816
	ds_read_b128 v[100:103], v140 offset:36864
	ds_read_b128 v[104:107], v140 offset:38912
	ds_read_b128 v[108:111], v143
	ds_read_b128 v[112:115], v143 offset:2048
	ds_read_b128 v[116:119], v143 offset:4096
	ds_read_b128 v[120:123], v143 offset:6144
	ds_read_b128 v[124:127], v142 offset:32768
	ds_read_b128 v[128:131], v142 offset:34816
	ds_read_b128 v[132:135], v142 offset:36864
	ds_read_b128 v[136:139], v142 offset:38912
	s_waitcnt lgkmcnt(0)
	v_mfma_f32_16x16x32_bf16 v[40:43], v[92:95], v[76:79], v[40:43]
	v_mfma_f32_16x16x32_bf16 v[60:63], v[96:99], v[76:79], v[60:63]
	v_mfma_f32_16x16x32_bf16 v[64:67], v[100:103], v[76:79], v[64:67]
	v_mfma_f32_16x16x32_bf16 v[12:15], v[104:107], v[76:79], v[12:15]
	v_mfma_f32_16x16x32_bf16 v[44:47], v[92:95], v[80:83], v[44:47]
	v_mfma_f32_16x16x32_bf16 v[52:55], v[96:99], v[80:83], v[52:55]
	v_mfma_f32_16x16x32_bf16 v[68:71], v[100:103], v[80:83], v[68:71]
	v_mfma_f32_16x16x32_bf16 v[16:19], v[104:107], v[80:83], v[16:19]
	v_mfma_f32_16x16x32_bf16 v[48:51], v[92:95], v[84:87], v[48:51]
	v_mfma_f32_16x16x32_bf16 v[56:59], v[96:99], v[84:87], v[56:59]
	v_mfma_f32_16x16x32_bf16 v[72:75], v[100:103], v[84:87], v[72:75]
	v_mfma_f32_16x16x32_bf16 v[20:23], v[104:107], v[84:87], v[20:23]
	v_mfma_f32_16x16x32_bf16 v[28:31], v[92:95], v[88:91], v[28:31]
	v_mfma_f32_16x16x32_bf16 v[32:35], v[96:99], v[88:91], v[32:35]
	v_mfma_f32_16x16x32_bf16 v[36:39], v[100:103], v[88:91], v[36:39]
	v_mfma_f32_16x16x32_bf16 v[24:27], v[104:107], v[88:91], v[24:27]
	v_mfma_f32_16x16x32_bf16 v[40:43], v[124:127], v[108:111], v[40:43]
	v_mfma_f32_16x16x32_bf16 v[60:63], v[128:131], v[108:111], v[60:63]
	v_mfma_f32_16x16x32_bf16 v[64:67], v[132:135], v[108:111], v[64:67]
	v_mfma_f32_16x16x32_bf16 v[12:15], v[136:139], v[108:111], v[12:15]
	v_mfma_f32_16x16x32_bf16 v[44:47], v[124:127], v[112:115], v[44:47]
	v_mfma_f32_16x16x32_bf16 v[52:55], v[128:131], v[112:115], v[52:55]
	v_mfma_f32_16x16x32_bf16 v[68:71], v[132:135], v[112:115], v[68:71]
	v_mfma_f32_16x16x32_bf16 v[16:19], v[136:139], v[112:115], v[16:19]
	v_mfma_f32_16x16x32_bf16 v[48:51], v[124:127], v[116:119], v[48:51]
	v_mfma_f32_16x16x32_bf16 v[56:59], v[128:131], v[116:119], v[56:59]
	v_mfma_f32_16x16x32_bf16 v[72:75], v[132:135], v[116:119], v[72:75]
	v_mfma_f32_16x16x32_bf16 v[20:23], v[136:139], v[116:119], v[20:23]
	v_mfma_f32_16x16x32_bf16 v[28:31], v[124:127], v[120:123], v[28:31]
	v_mfma_f32_16x16x32_bf16 v[32:35], v[128:131], v[120:123], v[32:35]
	v_mfma_f32_16x16x32_bf16 v[36:39], v[132:135], v[120:123], v[36:39]
	v_mfma_f32_16x16x32_bf16 v[24:27], v[136:139], v[120:123], v[24:27]
	s_mov_b32 m0, s19
	s_waitcnt vmcnt(6)
	s_mov_b64 s[18:19], 0x280
	s_waitcnt lgkmcnt(0)
	s_barrier
	v_lshl_add_u64 v[0:1], v[0:1], 0, s[18:19]
	global_load_lds_dwordx4 v[0:1], off
	v_lshl_add_u64 v[0:1], v[2:3], 0, s[18:19]
	s_mov_b32 m0, s3
	s_nop 0
	global_load_lds_dwordx4 v[0:1], off
	v_lshl_add_u64 v[0:1], v[4:5], 0, s[18:19]
	s_mov_b32 m0, s5
	s_nop 0
	global_load_lds_dwordx4 v[0:1], off
	v_lshl_add_u64 v[0:1], v[6:7], 0, s[18:19]
	s_mov_b32 m0, s13
	s_nop 0
	global_load_lds_dwordx4 v[0:1], off
	v_lshl_add_u64 v[0:1], v[10:11], 0, s[18:19]
	s_mov_b32 m0, s15
	s_nop 0
	global_load_lds_dwordx4 v[0:1], off
	v_lshl_add_u64 v[0:1], v[8:9], 0, s[18:19]
	s_mov_b32 m0, s17
	s_nop 0
	global_load_lds_dwordx4 v[0:1], off
	ds_read_b128 v[0:3], v144
	ds_read_b128 v[4:7], v144 offset:2048
	ds_read_b128 v[8:11], v144 offset:4096
	ds_read_b128 v[76:79], v144 offset:6144
	ds_read_b128 v[80:83], v145 offset:32768
	ds_read_b128 v[84:87], v145 offset:34816
	ds_read_b128 v[88:91], v145 offset:36864
	ds_read_b128 v[92:95], v145 offset:38912
	ds_read_b128 v[96:99], v147
	ds_read_b128 v[100:103], v147 offset:2048
	ds_read_b128 v[104:107], v147 offset:4096
	ds_read_b128 v[108:111], v147 offset:6144
	ds_read_b128 v[112:115], v146 offset:32768
	ds_read_b128 v[116:119], v146 offset:34816
	ds_read_b128 v[120:123], v146 offset:36864
	ds_read_b128 v[124:127], v146 offset:38912
	s_waitcnt lgkmcnt(0)
	v_mfma_f32_16x16x32_bf16 v[40:43], v[80:83], v[0:3], v[40:43]
	v_mfma_f32_16x16x32_bf16 v[60:63], v[84:87], v[0:3], v[60:63]
	v_mfma_f32_16x16x32_bf16 v[64:67], v[88:91], v[0:3], v[64:67]
	v_mfma_f32_16x16x32_bf16 v[0:3], v[92:95], v[0:3], v[12:15]
	v_mfma_f32_16x16x32_bf16 v[12:15], v[80:83], v[4:7], v[44:47]
	v_mfma_f32_16x16x32_bf16 v[44:47], v[84:87], v[4:7], v[52:55]
	v_mfma_f32_16x16x32_bf16 v[52:55], v[88:91], v[4:7], v[68:71]
	v_mfma_f32_16x16x32_bf16 v[4:7], v[92:95], v[4:7], v[16:19]
	v_mfma_f32_16x16x32_bf16 v[16:19], v[80:83], v[8:11], v[48:51]
	v_mfma_f32_16x16x32_bf16 v[48:51], v[84:87], v[8:11], v[56:59]
	v_mfma_f32_16x16x32_bf16 v[56:59], v[88:91], v[8:11], v[72:75]
	v_mfma_f32_16x16x32_bf16 v[8:11], v[92:95], v[8:11], v[20:23]
	v_mfma_f32_16x16x32_bf16 v[20:23], v[80:83], v[76:79], v[28:31]
	v_mfma_f32_16x16x32_bf16 v[28:31], v[84:87], v[76:79], v[32:35]
	v_mfma_f32_16x16x32_bf16 v[32:35], v[88:91], v[76:79], v[36:39]
	v_mfma_f32_16x16x32_bf16 v[24:27], v[92:95], v[76:79], v[24:27]
	v_mfma_f32_16x16x32_bf16 v[36:39], v[112:115], v[96:99], v[40:43]
	v_mfma_f32_16x16x32_bf16 v[40:43], v[116:119], v[96:99], v[60:63]
	v_mfma_f32_16x16x32_bf16 v[60:63], v[120:123], v[96:99], v[64:67]
	v_mfma_f32_16x16x32_bf16 v[0:3], v[124:127], v[96:99], v[0:3]
	v_mfma_f32_16x16x32_bf16 v[12:15], v[112:115], v[100:103], v[12:15]
	v_mfma_f32_16x16x32_bf16 v[44:47], v[116:119], v[100:103], v[44:47]
	v_mfma_f32_16x16x32_bf16 v[52:55], v[120:123], v[100:103], v[52:55]
	v_mfma_f32_16x16x32_bf16 v[4:7], v[124:127], v[100:103], v[4:7]
	v_mfma_f32_16x16x32_bf16 v[16:19], v[112:115], v[104:107], v[16:19]
	v_mfma_f32_16x16x32_bf16 v[48:51], v[116:119], v[104:107], v[48:51]
	v_mfma_f32_16x16x32_bf16 v[56:59], v[120:123], v[104:107], v[56:59]
	v_mfma_f32_16x16x32_bf16 v[8:11], v[124:127], v[104:107], v[8:11]
	v_mfma_f32_16x16x32_bf16 v[20:23], v[112:115], v[108:111], v[20:23]
	v_mfma_f32_16x16x32_bf16 v[28:31], v[116:119], v[108:111], v[28:31]
	v_mfma_f32_16x16x32_bf16 v[32:35], v[120:123], v[108:111], v[32:35]
	v_mfma_f32_16x16x32_bf16 v[24:27], v[124:127], v[108:111], v[24:27]
	s_waitcnt vmcnt(6)
	s_waitcnt lgkmcnt(0)
	s_barrier
	ds_read_b128 v[64:67], v144 offset:49152
	ds_read_b128 v[68:71], v144 offset:51200
	ds_read_b128 v[72:75], v144 offset:53248
	ds_read_b128 v[76:79], v144 offset:55296
	ds_read_b128 v[80:83], v148 offset:32768
	ds_read_b128 v[84:87], v148 offset:34816
	ds_read_b128 v[88:91], v148 offset:36864
	ds_read_b128 v[92:95], v148 offset:38912
	ds_read_b128 v[96:99], v147 offset:49152
	ds_read_b128 v[100:103], v147 offset:51200
	ds_read_b128 v[104:107], v147 offset:53248
	ds_read_b128 v[108:111], v147 offset:55296
	ds_read_b128 v[112:115], v149 offset:32768
	ds_read_b128 v[116:119], v149 offset:34816
	ds_read_b128 v[120:123], v149 offset:36864
	ds_read_b128 v[124:127], v149 offset:38912
	s_waitcnt lgkmcnt(0)
	v_mfma_f32_16x16x32_bf16 v[36:39], v[80:83], v[64:67], v[36:39]
	v_mfma_f32_16x16x32_bf16 v[40:43], v[84:87], v[64:67], v[40:43]
	v_mfma_f32_16x16x32_bf16 v[60:63], v[88:91], v[64:67], v[60:63]
	v_mfma_f32_16x16x32_bf16 v[0:3], v[92:95], v[64:67], v[0:3]
	v_mfma_f32_16x16x32_bf16 v[12:15], v[80:83], v[68:71], v[12:15]
	v_mfma_f32_16x16x32_bf16 v[44:47], v[84:87], v[68:71], v[44:47]
	v_mfma_f32_16x16x32_bf16 v[52:55], v[88:91], v[68:71], v[52:55]
	v_mfma_f32_16x16x32_bf16 v[4:7], v[92:95], v[68:71], v[4:7]
	v_mfma_f32_16x16x32_bf16 v[16:19], v[80:83], v[72:75], v[16:19]
	v_mfma_f32_16x16x32_bf16 v[48:51], v[84:87], v[72:75], v[48:51]
	v_mfma_f32_16x16x32_bf16 v[56:59], v[88:91], v[72:75], v[56:59]
	v_mfma_f32_16x16x32_bf16 v[8:11], v[92:95], v[72:75], v[8:11]
	v_mfma_f32_16x16x32_bf16 v[20:23], v[80:83], v[76:79], v[20:23]
	v_mfma_f32_16x16x32_bf16 v[28:31], v[84:87], v[76:79], v[28:31]
	v_mfma_f32_16x16x32_bf16 v[32:35], v[88:91], v[76:79], v[32:35]
	v_mfma_f32_16x16x32_bf16 v[24:27], v[92:95], v[76:79], v[24:27]
	v_mfma_f32_16x16x32_bf16 v[36:39], v[112:115], v[96:99], v[36:39]
	v_mfma_f32_16x16x32_bf16 v[40:43], v[116:119], v[96:99], v[40:43]
	v_mfma_f32_16x16x32_bf16 v[60:63], v[120:123], v[96:99], v[60:63]
	v_mfma_f32_16x16x32_bf16 v[0:3], v[124:127], v[96:99], v[0:3]
	v_mfma_f32_16x16x32_bf16 v[12:15], v[112:115], v[100:103], v[12:15]
	v_mfma_f32_16x16x32_bf16 v[44:47], v[116:119], v[100:103], v[44:47]
	v_mfma_f32_16x16x32_bf16 v[52:55], v[120:123], v[100:103], v[52:55]
	v_mfma_f32_16x16x32_bf16 v[4:7], v[124:127], v[100:103], v[4:7]
	v_mfma_f32_16x16x32_bf16 v[16:19], v[112:115], v[104:107], v[16:19]
	v_mfma_f32_16x16x32_bf16 v[48:51], v[116:119], v[104:107], v[48:51]
	v_mfma_f32_16x16x32_bf16 v[56:59], v[120:123], v[104:107], v[56:59]
	v_mfma_f32_16x16x32_bf16 v[8:11], v[124:127], v[104:107], v[8:11]
	v_mfma_f32_16x16x32_bf16 v[20:23], v[112:115], v[108:111], v[20:23]
	v_mfma_f32_16x16x32_bf16 v[28:31], v[116:119], v[108:111], v[28:31]
	v_mfma_f32_16x16x32_bf16 v[32:35], v[120:123], v[108:111], v[32:35]
	v_mfma_f32_16x16x32_bf16 v[24:27], v[124:127], v[108:111], v[24:27]
	s_waitcnt vmcnt(0)
	s_waitcnt lgkmcnt(0)
	s_barrier
	ds_read_b128 v[64:67], v141
	ds_read_b128 v[68:71], v141 offset:2048
	ds_read_b128 v[72:75], v141 offset:4096
	ds_read_b128 v[76:79], v141 offset:6144
	ds_read_b128 v[80:83], v140 offset:32768
	ds_read_b128 v[84:87], v140 offset:34816
	ds_read_b128 v[88:91], v140 offset:36864
	ds_read_b128 v[92:95], v140 offset:38912
	ds_read_b128 v[96:99], v143
	ds_read_b128 v[100:103], v143 offset:2048
	ds_read_b128 v[104:107], v143 offset:4096
	ds_read_b128 v[108:111], v143 offset:6144
	ds_read_b128 v[112:115], v142 offset:32768
	ds_read_b128 v[116:119], v142 offset:34816
	ds_read_b128 v[120:123], v142 offset:36864
	ds_read_b128 v[124:127], v142 offset:38912
	s_waitcnt lgkmcnt(0)
	v_mfma_f32_16x16x32_bf16 v[36:39], v[80:83], v[64:67], v[36:39]
	v_mfma_f32_16x16x32_bf16 v[40:43], v[84:87], v[64:67], v[40:43]
	v_mfma_f32_16x16x32_bf16 v[60:63], v[88:91], v[64:67], v[60:63]
	v_mfma_f32_16x16x32_bf16 v[0:3], v[92:95], v[64:67], v[0:3]
	v_mfma_f32_16x16x32_bf16 v[12:15], v[80:83], v[68:71], v[12:15]
	v_mfma_f32_16x16x32_bf16 v[44:47], v[84:87], v[68:71], v[44:47]
	v_mfma_f32_16x16x32_bf16 v[52:55], v[88:91], v[68:71], v[52:55]
	v_mfma_f32_16x16x32_bf16 v[4:7], v[92:95], v[68:71], v[4:7]
	v_mfma_f32_16x16x32_bf16 v[16:19], v[80:83], v[72:75], v[16:19]
	v_mfma_f32_16x16x32_bf16 v[48:51], v[84:87], v[72:75], v[48:51]
	v_mfma_f32_16x16x32_bf16 v[56:59], v[88:91], v[72:75], v[56:59]
	v_mfma_f32_16x16x32_bf16 v[8:11], v[92:95], v[72:75], v[8:11]
	v_mfma_f32_16x16x32_bf16 v[20:23], v[80:83], v[76:79], v[20:23]
	v_mfma_f32_16x16x32_bf16 v[28:31], v[84:87], v[76:79], v[28:31]
	v_mfma_f32_16x16x32_bf16 v[32:35], v[88:91], v[76:79], v[32:35]
	v_mfma_f32_16x16x32_bf16 v[24:27], v[92:95], v[76:79], v[24:27]
	v_mfma_f32_16x16x32_bf16 v[36:39], v[112:115], v[96:99], v[36:39]
	v_mfma_f32_16x16x32_bf16 v[40:43], v[116:119], v[96:99], v[40:43]
	v_mfma_f32_16x16x32_bf16 v[60:63], v[120:123], v[96:99], v[60:63]
	v_mfma_f32_16x16x32_bf16 v[64:67], v[124:127], v[96:99], v[0:3]
	v_mfma_f32_16x16x32_bf16 v[12:15], v[112:115], v[100:103], v[12:15]
	v_mfma_f32_16x16x32_bf16 v[44:47], v[116:119], v[100:103], v[44:47]
	v_mfma_f32_16x16x32_bf16 v[52:55], v[120:123], v[100:103], v[52:55]
	v_mfma_f32_16x16x32_bf16 v[68:71], v[124:127], v[100:103], v[4:7]
	v_mfma_f32_16x16x32_bf16 v[16:19], v[112:115], v[104:107], v[16:19]
	v_mfma_f32_16x16x32_bf16 v[48:51], v[116:119], v[104:107], v[48:51]
	v_mfma_f32_16x16x32_bf16 v[56:59], v[120:123], v[104:107], v[56:59]
	v_mfma_f32_16x16x32_bf16 v[8:11], v[124:127], v[104:107], v[8:11]
	v_mfma_f32_16x16x32_bf16 v[20:23], v[112:115], v[108:111], v[20:23]
	v_mfma_f32_16x16x32_bf16 v[28:31], v[116:119], v[108:111], v[28:31]
	v_mfma_f32_16x16x32_bf16 v[4:7], v[120:123], v[108:111], v[32:35]
	v_mfma_f32_16x16x32_bf16 v[0:3], v[124:127], v[108:111], v[24:27]
	s_waitcnt vmcnt(0)
	s_nop 2
	v_mov_b32_e32 v24, v204
	s_waitcnt lgkmcnt(0)
	s_barrier
	v_readlane_b32 s2, v252, 54
	v_ashrrev_i32_e32 v25, 1, v24
	v_and_b32_e32 v25, 0xffffffc0, v25
	v_and_or_b32 v26, v24, 15, s11
	v_add_u32_e32 v25, v26, v25
	v_and_b32_e32 v26, 64, v24
	v_lshrrev_b32_e32 v24, 2, v24
	v_and_b32_e32 v24, 12, v24
	v_or3_b32 v24, v26, v24, s0
	v_subrev_u32_e32 v26, s11, v25
	s_add_i32 s0, 0, 0x24000
	v_lshl_add_u32 v26, v26, 2, s0
	s_waitcnt vmcnt(0)
	ds_read_b32 v26, v26
	v_or_b32_e32 v33, 16, v25
	v_subrev_u32_e32 v27, s11, v33
	v_or_b32_e32 v35, 32, v25
	v_lshl_add_u32 v27, v27, 2, s0
	v_subrev_u32_e32 v32, s11, v35
	v_or_b32_e32 v73, 48, v25
	v_lshl_add_u32 v34, v32, 2, s0
	v_subrev_u32_e32 v32, s11, v73
	s_waitcnt lgkmcnt(0)
	v_pk_mul_f32 v[38:39], v[38:39], v[26:27] op_sel_hi:[1,0]
	v_pk_mul_f32 v[36:37], v[36:37], v[26:27] op_sel_hi:[1,0]
	v_readlane_b32 s3, v252, 55
	v_lshl_add_u32 v72, v32, 2, s0
	v_cvt_pk_bf16_f32 v36, v36, v37
	v_cvt_pk_bf16_f32 v37, v38, v39
	v_mov_b64_e32 v[38:39], s[2:3]
	s_movk_i32 s0, 0x600
	v_mad_i64_i32 v[74:75], s[2:3], v25, s0, v[38:39]
	v_ashrrev_i32_e32 v25, 31, v24
	v_lshlrev_b64 v[24:25], 1, v[24:25]
	ds_read_b32 v32, v27
	ds_read_b32 v34, v34
	ds_read_b32 v72, v72
	v_lshl_add_u64 v[74:75], v[74:75], 0, v[24:25]
	v_and_b32_e32 v230, 16, v204
	v_lshrrev_b32_e32 v231, 1, v230
	v_add_u32_e32 v230, v230, v231
	v_mov_b32_e32 v231, v189
	v_mov_b64_e32 v[232:233], v[36:37]
	v_pk_mul_f32 v[36:37], v[42:43], v[26:27] op_sel_hi:[1,0]
	v_pk_mul_f32 v[40:41], v[40:41], v[26:27] op_sel_hi:[1,0]
	s_waitcnt lgkmcnt(2)
	v_pk_mul_f32 v[14:15], v[14:15], v[32:33] op_sel_hi:[1,0]
	v_cvt_pk_bf16_f32 v40, v40, v41
	v_cvt_pk_bf16_f32 v41, v36, v37
	v_mov_b64_e32 v[234:235], v[40:41]
	s_nop 1
	v_permlane16_swap_b32 v232, v234
	v_permlane16_swap_b32 v233, v235
	v_lshl_add_u64 v[248:249], v[74:75], 0, v[230:231]
	global_store_dwordx4 v[248:249], v[232:235], off
	s_nop 1
	v_pk_mul_f32 v[36:37], v[62:63], v[26:27] op_sel_hi:[1,0]
	v_pk_mul_f32 v[40:41], v[60:61], v[26:27] op_sel_hi:[1,0]
	v_pk_mul_f32 v[12:13], v[12:13], v[32:33] op_sel_hi:[1,0]
	v_cvt_pk_bf16_f32 v40, v40, v41
	v_cvt_pk_bf16_f32 v41, v36, v37
	v_pk_mul_f32 v[36:37], v[66:67], v[26:27] op_sel_hi:[1,0]
	v_pk_mul_f32 v[26:27], v[64:65], v[26:27] op_sel_hi:[1,0]
	v_cvt_pk_bf16_f32 v12, v12, v13
	v_cvt_pk_bf16_f32 v13, v14, v15
	v_mad_i64_i32 v[14:15], s[2:3], v33, s0, v[38:39]
	v_cvt_pk_bf16_f32 v26, v26, v27
	v_cvt_pk_bf16_f32 v27, v36, v37
	v_lshl_add_u64 v[14:15], v[14:15], 0, v[24:25]
	v_mov_b64_e32 v[234:235], v[26:27]
	v_mov_b64_e32 v[236:237], v[12:13]
	v_pk_mul_f32 v[12:13], v[46:47], v[32:33] op_sel_hi:[1,0]
	v_pk_mul_f32 v[26:27], v[44:45], v[32:33] op_sel_hi:[1,0]
	s_waitcnt lgkmcnt(1)
	v_pk_mul_f32 v[10:11], v[10:11], v[34:35] op_sel_hi:[1,0]
	v_cvt_pk_bf16_f32 v26, v26, v27
	v_cvt_pk_bf16_f32 v27, v12, v13
	v_mov_b64_e32 v[238:239], v[26:27]
	s_nop 1
	v_permlane16_swap_b32 v236, v238
	v_permlane16_swap_b32 v237, v239
	v_lshl_add_u64 v[248:249], v[14:15], 0, v[230:231]
	global_store_dwordx4 v[248:249], v[236:239], off
	s_nop 1
	v_pk_mul_f32 v[12:13], v[54:55], v[32:33] op_sel_hi:[1,0]
	v_pk_mul_f32 v[26:27], v[52:53], v[32:33] op_sel_hi:[1,0]
	v_pk_mul_f32 v[8:9], v[8:9], v[34:35] op_sel_hi:[1,0]
	v_cvt_pk_bf16_f32 v26, v26, v27
	v_cvt_pk_bf16_f32 v27, v12, v13
	v_mov_b64_e32 v[236:237], v[26:27]
	v_pk_mul_f32 v[12:13], v[70:71], v[32:33] op_sel_hi:[1,0]
	v_pk_mul_f32 v[26:27], v[68:69], v[32:33] op_sel_hi:[1,0]
	v_cvt_pk_bf16_f32 v8, v8, v9
	v_cvt_pk_bf16_f32 v26, v26, v27
	v_cvt_pk_bf16_f32 v27, v12, v13
	v_mov_b64_e32 v[238:239], v[26:27]
	s_nop 1
	v_permlane16_swap_b32 v236, v238
	v_permlane16_swap_b32 v237, v239
	v_lshl_add_u64 v[248:249], v[14:15], 0, v[230:231]
	global_store_dwordx4 v[248:249], v[236:239], off offset:64
	s_nop 1
	v_pk_mul_f32 v[12:13], v[18:19], v[34:35] op_sel_hi:[1,0]
	v_pk_mul_f32 v[14:15], v[16:17], v[34:35] op_sel_hi:[1,0]
	v_pk_mul_f32 v[16:17], v[48:49], v[34:35] op_sel_hi:[1,0]
	v_cvt_pk_bf16_f32 v14, v14, v15
	v_cvt_pk_bf16_f32 v15, v12, v13
	v_mad_i64_i32 v[12:13], s[2:3], v35, s0, v[38:39]
	v_lshl_add_u64 v[12:13], v[12:13], 0, v[24:25]
	v_mov_b64_e32 v[236:237], v[14:15]
	v_pk_mul_f32 v[14:15], v[50:51], v[34:35] op_sel_hi:[1,0]
	v_cvt_pk_bf16_f32 v9, v10, v11
	v_cvt_pk_bf16_f32 v16, v16, v17
	v_cvt_pk_bf16_f32 v17, v14, v15
	v_mov_b64_e32 v[242:243], v[8:9]
	s_waitcnt lgkmcnt(0)
	v_pk_mul_f32 v[8:9], v[22:23], v[72:73] op_sel_hi:[1,0]
	v_pk_mul_f32 v[10:11], v[20:21], v[72:73] op_sel_hi:[1,0]
	v_mov_b64_e32 v[238:239], v[16:17]
	s_nop 1
	v_permlane16_swap_b32 v236, v238
	v_permlane16_swap_b32 v237, v239
	v_lshl_add_u64 v[248:249], v[12:13], 0, v[230:231]
	global_store_dwordx4 v[248:249], v[236:239], off
	s_nop 1
	v_pk_mul_f32 v[14:15], v[58:59], v[34:35] op_sel_hi:[1,0]
	v_pk_mul_f32 v[16:17], v[56:57], v[34:35] op_sel_hi:[1,0]
	v_cvt_pk_bf16_f32 v10, v10, v11
	v_cvt_pk_bf16_f32 v11, v8, v9
	v_mad_i64_i32 v[8:9], s[2:3], v73, s0, v[38:39]
	v_cvt_pk_bf16_f32 v16, v16, v17
	v_cvt_pk_bf16_f32 v17, v14, v15
	v_lshl_add_u64 v[8:9], v[8:9], 0, v[24:25]
	v_mov_b64_e32 v[240:241], v[16:17]
	s_nop 1
	v_permlane16_swap_b32 v240, v242
	v_permlane16_swap_b32 v241, v243
	v_lshl_add_u64 v[248:249], v[12:13], 0, v[230:231]
	global_store_dwordx4 v[248:249], v[240:243], off offset:64
	s_nop 1
	v_mov_b64_e32 v[236:237], v[10:11]
	v_pk_mul_f32 v[10:11], v[30:31], v[72:73] op_sel_hi:[1,0]
	v_pk_mul_f32 v[12:13], v[28:29], v[72:73] op_sel_hi:[1,0]
	v_pk_mul_f32 v[6:7], v[6:7], v[72:73] op_sel_hi:[1,0]
	v_pk_mul_f32 v[4:5], v[4:5], v[72:73] op_sel_hi:[1,0]
	v_pk_mul_f32 v[2:3], v[2:3], v[72:73] op_sel_hi:[1,0]
	v_pk_mul_f32 v[0:1], v[0:1], v[72:73] op_sel_hi:[1,0]
	v_cvt_pk_bf16_f32 v12, v12, v13
	v_cvt_pk_bf16_f32 v13, v10, v11
	v_cvt_pk_bf16_f32 v4, v4, v5
	v_cvt_pk_bf16_f32 v5, v6, v7
	v_cvt_pk_bf16_f32 v0, v0, v1
	v_cvt_pk_bf16_f32 v1, v2, v3
	v_mov_b64_e32 v[232:233], v[40:41]
	s_nop 1
	v_permlane16_swap_b32 v232, v234
	v_permlane16_swap_b32 v233, v235
	v_lshl_add_u64 v[248:249], v[74:75], 0, v[230:231]
	global_store_dwordx4 v[248:249], v[232:235], off offset:64
	s_nop 1
	v_mov_b64_e32 v[238:239], v[12:13]
	s_nop 1
	v_permlane16_swap_b32 v236, v238
	v_permlane16_swap_b32 v237, v239
	v_lshl_add_u64 v[248:249], v[8:9], 0, v[230:231]
	global_store_dwordx4 v[248:249], v[236:239], off
	s_nop 1
	v_mov_b64_e32 v[232:233], v[4:5]
	v_mov_b64_e32 v[234:235], v[0:1]
	s_nop 1
	v_permlane16_swap_b32 v232, v234
	v_permlane16_swap_b32 v233, v235
	v_lshl_add_u64 v[248:249], v[8:9], 0, v[230:231]
	global_store_dwordx4 v[248:249], v[232:235], off offset:64
	s_nop 1
	s_branch .LBB0_263

.LBB0_372:
	s_add_u32 s4, s2, 0xfffc0080
	s_addc_u32 s5, s3, -1
	s_add_i32 s36, 0, 0x10000
	v_add_u32_e32 v145, s36, v143
	ds_read_b128 v[138:141], v145
	ds_read_b128 v[146:149], v145 offset:1024
	ds_read_b128 v[150:153], v145 offset:2048
	ds_read_b128 v[154:157], v145 offset:3072
	s_cmp_eq_u32 s35, 12
	s_cselect_b32 s7, s10, s5
	s_cselect_b32 s6, s11, s4
	s_cselect_b32 s5, s13, s23
	s_cselect_b32 s4, s15, s22
	v_lshl_add_u64 v[186:187], s[2:3], 0, v[134:135]
	s_add_i32 m0, s25, 0xc000
	ds_read_b128 v[158:161], v144
	ds_read_b128 v[162:165], v144 offset:1024
	ds_read_b128 v[166:169], v144 offset:2048
	ds_read_b128 v[170:173], v144 offset:3072
	ds_read_b128 v[174:177], v144 offset:4096
	ds_read_b128 v[178:181], v144 offset:5120
	ds_read_b128 v[182:185], v144 offset:6144
	ds_read_b128 v[190:193], v144 offset:7168
	global_load_lds_dwordx4 v[186:187], off
	v_lshl_add_u64 v[186:187], s[2:3], 0, v[136:137]
	s_add_i32 m0, s25, 0xe000
	s_nop 0
	global_load_lds_dwordx4 v[186:187], off
	s_waitcnt lgkmcnt(8)
	s_barrier
	s_waitcnt lgkmcnt(0)
	s_setprio 1
	s_waitcnt lgkmcnt(0)
	v_mfma_f32_16x16x32_bf16 v[124:127], v[138:141], v[158:161], v[124:127]
	v_mfma_f32_16x16x32_bf16 v[120:123], v[150:153], v[158:161], v[120:123]
	v_mfma_f32_16x16x32_bf16 v[108:111], v[138:141], v[166:169], v[108:111]
	v_mfma_f32_16x16x32_bf16 v[104:107], v[150:153], v[166:169], v[104:107]
	v_mfma_f32_16x16x32_bf16 v[92:95], v[138:141], v[174:177], v[92:95]
	v_mfma_f32_16x16x32_bf16 v[88:91], v[150:153], v[174:177], v[88:91]
	v_mfma_f32_16x16x32_bf16 v[76:79], v[138:141], v[182:185], v[76:79]
	v_mfma_f32_16x16x32_bf16 v[72:75], v[150:153], v[182:185], v[72:75]
	v_mfma_f32_16x16x32_bf16 v[124:127], v[146:149], v[162:165], v[124:127]
	v_mfma_f32_16x16x32_bf16 v[120:123], v[154:157], v[162:165], v[120:123]
	v_mfma_f32_16x16x32_bf16 v[108:111], v[146:149], v[170:173], v[108:111]
	v_mfma_f32_16x16x32_bf16 v[104:107], v[154:157], v[170:173], v[104:107]
	v_mfma_f32_16x16x32_bf16 v[92:95], v[146:149], v[178:181], v[92:95]
	v_mfma_f32_16x16x32_bf16 v[88:91], v[154:157], v[178:181], v[88:91]
	v_mfma_f32_16x16x32_bf16 v[76:79], v[146:149], v[190:193], v[76:79]
	v_mfma_f32_16x16x32_bf16 v[72:75], v[154:157], v[190:193], v[72:75]
	s_setprio 0
	s_barrier
	s_add_i32 s38, 0, 0x14000
	s_add_i32 s36, s36, s24
	v_add_u32_e32 v145, s38, v143
	v_lshl_add_u64 v[186:187], s[4:5], 0, v[130:131]
	s_mov_b32 m0, s36
	ds_read_b128 v[194:197], v145
	ds_read_b128 v[198:201], v145 offset:1024
	ds_read_b128 v[216:219], v145 offset:2048
	ds_read_b128 v[220:223], v145 offset:3072
	global_load_lds_dwordx4 v[186:187], off
	v_lshl_add_u64 v[202:203], s[4:5], 0, v[128:129]
	s_add_i32 m0, s36, 0x2000
	s_nop 0
	global_load_lds_dwordx4 v[202:203], off
	s_barrier
	s_waitcnt lgkmcnt(0)
	s_setprio 1
	s_waitcnt lgkmcnt(0)
	v_mfma_f32_16x16x32_bf16 v[116:119], v[194:197], v[158:161], v[116:119]
	v_mfma_f32_16x16x32_bf16 v[112:115], v[216:219], v[158:161], v[112:115]
	v_mfma_f32_16x16x32_bf16 v[100:103], v[194:197], v[166:169], v[100:103]
	v_mfma_f32_16x16x32_bf16 v[96:99], v[216:219], v[166:169], v[96:99]
	v_mfma_f32_16x16x32_bf16 v[84:87], v[194:197], v[174:177], v[84:87]
	v_mfma_f32_16x16x32_bf16 v[80:83], v[216:219], v[174:177], v[80:83]
	v_mfma_f32_16x16x32_bf16 v[68:71], v[194:197], v[182:185], v[68:71]
	v_mfma_f32_16x16x32_bf16 v[64:67], v[216:219], v[182:185], v[64:67]
	v_mfma_f32_16x16x32_bf16 v[116:119], v[198:201], v[162:165], v[116:119]
	v_mfma_f32_16x16x32_bf16 v[112:115], v[220:223], v[162:165], v[112:115]
	v_mfma_f32_16x16x32_bf16 v[100:103], v[198:201], v[170:173], v[100:103]
	v_mfma_f32_16x16x32_bf16 v[96:99], v[220:223], v[170:173], v[96:99]
	v_mfma_f32_16x16x32_bf16 v[84:87], v[198:201], v[178:181], v[84:87]
	v_mfma_f32_16x16x32_bf16 v[80:83], v[220:223], v[178:181], v[80:83]
	v_mfma_f32_16x16x32_bf16 v[68:71], v[198:201], v[190:193], v[68:71]
	v_mfma_f32_16x16x32_bf16 v[64:67], v[220:223], v[190:193], v[64:67]
	s_setprio 0
	s_mov_b32 m0, s25
	v_lshl_add_u64 v[224:225], s[6:7], 0, v[130:131]
	s_barrier
	ds_read_b128 v[158:161], v144 offset:16384
	ds_read_b128 v[162:165], v144 offset:17408
	ds_read_b128 v[166:169], v144 offset:18432
	ds_read_b128 v[170:173], v144 offset:19456
	ds_read_b128 v[174:177], v144 offset:20480
	ds_read_b128 v[178:181], v144 offset:21504
	ds_read_b128 v[182:185], v144 offset:22528
	ds_read_b128 v[190:193], v144 offset:23552
	global_load_lds_dwordx4 v[224:225], off
	v_lshl_add_u64 v[226:227], s[6:7], 0, v[128:129]
	s_mov_b32 m0, s26
	s_nop 0
	global_load_lds_dwordx4 v[226:227], off
	s_barrier
	s_waitcnt lgkmcnt(0)
	s_setprio 1
	s_waitcnt lgkmcnt(0)
	v_mfma_f32_16x16x32_bf16 v[60:63], v[138:141], v[158:161], v[60:63]
	v_mfma_f32_16x16x32_bf16 v[56:59], v[150:153], v[158:161], v[56:59]
	v_mfma_f32_16x16x32_bf16 v[44:47], v[138:141], v[166:169], v[44:47]
	v_mfma_f32_16x16x32_bf16 v[40:43], v[150:153], v[166:169], v[40:43]
	v_mfma_f32_16x16x32_bf16 v[28:31], v[138:141], v[174:177], v[28:31]
	v_mfma_f32_16x16x32_bf16 v[24:27], v[150:153], v[174:177], v[24:27]
	v_mfma_f32_16x16x32_bf16 v[12:15], v[138:141], v[182:185], v[12:15]
	v_mfma_f32_16x16x32_bf16 v[8:11], v[150:153], v[182:185], v[8:11]
	v_mfma_f32_16x16x32_bf16 v[60:63], v[146:149], v[162:165], v[60:63]
	v_mfma_f32_16x16x32_bf16 v[56:59], v[154:157], v[162:165], v[56:59]
	v_mfma_f32_16x16x32_bf16 v[44:47], v[146:149], v[170:173], v[44:47]
	v_mfma_f32_16x16x32_bf16 v[40:43], v[154:157], v[170:173], v[40:43]
	v_mfma_f32_16x16x32_bf16 v[28:31], v[146:149], v[178:181], v[28:31]
	v_mfma_f32_16x16x32_bf16 v[24:27], v[154:157], v[178:181], v[24:27]
	v_mfma_f32_16x16x32_bf16 v[12:15], v[146:149], v[190:193], v[12:15]
	v_mfma_f32_16x16x32_bf16 v[8:11], v[154:157], v[190:193], v[8:11]
	s_setprio 0
	s_barrier
	s_add_u32 s36, s4, 0x40000
	s_addc_u32 s37, s5, 0
	s_add_i32 s38, s38, s24
	v_lshl_add_u64 v[138:139], s[36:37], 0, v[130:131]
	s_mov_b32 m0, s38
	s_nop 0
	global_load_lds_dwordx4 v[138:139], off
	v_lshl_add_u64 v[138:139], s[36:37], 0, v[128:129]
	s_add_i32 m0, s38, 0x2000
	s_nop 0
	global_load_lds_dwordx4 v[138:139], off
	s_waitcnt vmcnt(6)
	s_barrier
	s_setprio 1
	v_mfma_f32_16x16x32_bf16 v[52:55], v[194:197], v[158:161], v[52:55]
	v_mfma_f32_16x16x32_bf16 v[48:51], v[216:219], v[158:161], v[48:51]
	v_mfma_f32_16x16x32_bf16 v[36:39], v[194:197], v[166:169], v[36:39]
	v_mfma_f32_16x16x32_bf16 v[32:35], v[216:219], v[166:169], v[32:35]
	v_mfma_f32_16x16x32_bf16 v[20:23], v[194:197], v[174:177], v[20:23]
	v_mfma_f32_16x16x32_bf16 v[16:19], v[216:219], v[174:177], v[16:19]
	v_mfma_f32_16x16x32_bf16 v[4:7], v[194:197], v[182:185], v[4:7]
	v_mfma_f32_16x16x32_bf16 v[0:3], v[216:219], v[182:185], v[0:3]
	v_mfma_f32_16x16x32_bf16 v[52:55], v[198:201], v[162:165], v[52:55]
	v_mfma_f32_16x16x32_bf16 v[48:51], v[220:223], v[162:165], v[48:51]
	v_mfma_f32_16x16x32_bf16 v[36:39], v[198:201], v[170:173], v[36:39]
	v_mfma_f32_16x16x32_bf16 v[32:35], v[220:223], v[170:173], v[32:35]
	v_mfma_f32_16x16x32_bf16 v[20:23], v[198:201], v[178:181], v[20:23]
	v_mfma_f32_16x16x32_bf16 v[16:19], v[220:223], v[178:181], v[16:19]
	v_mfma_f32_16x16x32_bf16 v[4:7], v[198:201], v[190:193], v[4:7]
	v_mfma_f32_16x16x32_bf16 v[0:3], v[220:223], v[190:193], v[0:3]
	s_setprio 0
	s_add_i32 s36, 0, 0x18000
	v_add_u32_e32 v145, s36, v143
	s_barrier
	ds_read_b128 v[138:141], v145
	ds_read_b128 v[146:149], v145 offset:1024
	ds_read_b128 v[150:153], v145 offset:2048
	ds_read_b128 v[154:157], v145 offset:3072
	s_add_u32 s6, s6, 0x40000
	s_addc_u32 s7, s7, 0
	s_mov_b32 m0, s27
	v_lshl_add_u64 v[194:195], s[6:7], 0, v[130:131]
	ds_read_b128 v[158:161], v144 offset:32768
	ds_read_b128 v[162:165], v144 offset:33792
	ds_read_b128 v[166:169], v144 offset:34816
	ds_read_b128 v[170:173], v144 offset:35840
	ds_read_b128 v[174:177], v144 offset:36864
	ds_read_b128 v[178:181], v144 offset:37888
	ds_read_b128 v[182:185], v144 offset:38912
	ds_read_b128 v[190:193], v144 offset:39936
	global_load_lds_dwordx4 v[194:195], off
	v_lshl_add_u64 v[194:195], s[6:7], 0, v[128:129]
	s_mov_b32 m0, s28
	s_nop 0
	global_load_lds_dwordx4 v[194:195], off
	s_waitcnt lgkmcnt(8)
	s_barrier
	s_waitcnt lgkmcnt(0)
	s_setprio 1
	s_waitcnt lgkmcnt(0)
	v_mfma_f32_16x16x32_bf16 v[124:127], v[138:141], v[158:161], v[124:127]
	v_mfma_f32_16x16x32_bf16 v[120:123], v[150:153], v[158:161], v[120:123]
	v_mfma_f32_16x16x32_bf16 v[108:111], v[138:141], v[166:169], v[108:111]
	v_mfma_f32_16x16x32_bf16 v[104:107], v[150:153], v[166:169], v[104:107]
	v_mfma_f32_16x16x32_bf16 v[92:95], v[138:141], v[174:177], v[92:95]
	v_mfma_f32_16x16x32_bf16 v[88:91], v[150:153], v[174:177], v[88:91]
	v_mfma_f32_16x16x32_bf16 v[76:79], v[138:141], v[182:185], v[76:79]
	v_mfma_f32_16x16x32_bf16 v[72:75], v[150:153], v[182:185], v[72:75]
	v_mfma_f32_16x16x32_bf16 v[124:127], v[146:149], v[162:165], v[124:127]
	v_mfma_f32_16x16x32_bf16 v[120:123], v[154:157], v[162:165], v[120:123]
	v_mfma_f32_16x16x32_bf16 v[108:111], v[146:149], v[170:173], v[108:111]
	v_mfma_f32_16x16x32_bf16 v[104:107], v[154:157], v[170:173], v[104:107]
	v_mfma_f32_16x16x32_bf16 v[92:95], v[146:149], v[178:181], v[92:95]
	v_mfma_f32_16x16x32_bf16 v[88:91], v[154:157], v[178:181], v[88:91]
	v_mfma_f32_16x16x32_bf16 v[76:79], v[146:149], v[190:193], v[76:79]
	v_mfma_f32_16x16x32_bf16 v[72:75], v[154:157], v[190:193], v[72:75]
	s_setprio 0
	s_barrier
	s_add_i32 s6, 0, 0x1c000
	s_add_i32 s7, s36, s24
	v_add_u32_e32 v145, s6, v143
	v_lshl_add_u64 v[186:187], v[186:187], 0, s[92:93]
	s_mov_b32 m0, s7
	ds_read_b128 v[194:197], v145
	ds_read_b128 v[198:201], v145 offset:1024
	ds_read_b128 v[216:219], v145 offset:2048
	ds_read_b128 v[220:223], v145 offset:3072
	global_load_lds_dwordx4 v[186:187], off
	v_lshl_add_u64 v[186:187], v[202:203], 0, s[92:93]
	s_add_i32 m0, s7, 0x2000
	s_nop 0
	global_load_lds_dwordx4 v[186:187], off
	s_barrier
	s_waitcnt lgkmcnt(0)
	s_setprio 1
	s_waitcnt lgkmcnt(0)
	v_mfma_f32_16x16x32_bf16 v[116:119], v[194:197], v[158:161], v[116:119]
	v_mfma_f32_16x16x32_bf16 v[112:115], v[216:219], v[158:161], v[112:115]
	v_mfma_f32_16x16x32_bf16 v[100:103], v[194:197], v[166:169], v[100:103]
	v_mfma_f32_16x16x32_bf16 v[96:99], v[216:219], v[166:169], v[96:99]
	v_mfma_f32_16x16x32_bf16 v[84:87], v[194:197], v[174:177], v[84:87]
	v_mfma_f32_16x16x32_bf16 v[80:83], v[216:219], v[174:177], v[80:83]
	v_mfma_f32_16x16x32_bf16 v[68:71], v[194:197], v[182:185], v[68:71]
	v_mfma_f32_16x16x32_bf16 v[64:67], v[216:219], v[182:185], v[64:67]
	v_mfma_f32_16x16x32_bf16 v[116:119], v[198:201], v[162:165], v[116:119]
	v_mfma_f32_16x16x32_bf16 v[112:115], v[220:223], v[162:165], v[112:115]
	v_mfma_f32_16x16x32_bf16 v[100:103], v[198:201], v[170:173], v[100:103]
	v_mfma_f32_16x16x32_bf16 v[96:99], v[220:223], v[170:173], v[96:99]
	v_mfma_f32_16x16x32_bf16 v[84:87], v[198:201], v[178:181], v[84:87]
	v_mfma_f32_16x16x32_bf16 v[80:83], v[220:223], v[178:181], v[80:83]
	v_mfma_f32_16x16x32_bf16 v[68:71], v[198:201], v[190:193], v[68:71]
	v_mfma_f32_16x16x32_bf16 v[64:67], v[220:223], v[190:193], v[64:67]
	s_setprio 0
	s_mov_b32 m0, s31
	v_lshl_add_u64 v[186:187], v[224:225], 0, s[92:93]
	s_barrier
	ds_read_b128 v[158:161], v144 offset:49152
	ds_read_b128 v[162:165], v144 offset:50176
	ds_read_b128 v[166:169], v144 offset:51200
	ds_read_b128 v[170:173], v144 offset:52224
	ds_read_b128 v[174:177], v144 offset:53248
	ds_read_b128 v[178:181], v144 offset:54272
	ds_read_b128 v[182:185], v144 offset:55296
	ds_read_b128 v[190:193], v144 offset:56320
	global_load_lds_dwordx4 v[186:187], off
	v_lshl_add_u64 v[186:187], v[226:227], 0, s[92:93]
	s_mov_b32 m0, s33
	s_nop 0
	global_load_lds_dwordx4 v[186:187], off
	s_barrier
	s_waitcnt lgkmcnt(0)
	s_setprio 1
	s_waitcnt lgkmcnt(0)
	v_mfma_f32_16x16x32_bf16 v[60:63], v[138:141], v[158:161], v[60:63]
	v_mfma_f32_16x16x32_bf16 v[56:59], v[150:153], v[158:161], v[56:59]
	v_mfma_f32_16x16x32_bf16 v[44:47], v[138:141], v[166:169], v[44:47]
	v_mfma_f32_16x16x32_bf16 v[40:43], v[150:153], v[166:169], v[40:43]
	v_mfma_f32_16x16x32_bf16 v[28:31], v[138:141], v[174:177], v[28:31]
	v_mfma_f32_16x16x32_bf16 v[24:27], v[150:153], v[174:177], v[24:27]
	v_mfma_f32_16x16x32_bf16 v[12:15], v[138:141], v[182:185], v[12:15]
	v_mfma_f32_16x16x32_bf16 v[8:11], v[150:153], v[182:185], v[8:11]
	v_mfma_f32_16x16x32_bf16 v[60:63], v[146:149], v[162:165], v[60:63]
	v_mfma_f32_16x16x32_bf16 v[56:59], v[154:157], v[162:165], v[56:59]
	v_mfma_f32_16x16x32_bf16 v[44:47], v[146:149], v[170:173], v[44:47]
	v_mfma_f32_16x16x32_bf16 v[40:43], v[154:157], v[170:173], v[40:43]
	v_mfma_f32_16x16x32_bf16 v[28:31], v[146:149], v[178:181], v[28:31]
	v_mfma_f32_16x16x32_bf16 v[24:27], v[154:157], v[178:181], v[24:27]
	v_mfma_f32_16x16x32_bf16 v[12:15], v[146:149], v[190:193], v[12:15]
	v_mfma_f32_16x16x32_bf16 v[8:11], v[154:157], v[190:193], v[8:11]
	s_setprio 0
	s_barrier
	s_add_u32 s4, s4, 0x40080
	s_addc_u32 s5, s5, 0
	s_add_i32 s6, s6, s24
	v_lshl_add_u64 v[138:139], s[4:5], 0, v[130:131]
	s_mov_b32 m0, s6
	s_nop 0
	global_load_lds_dwordx4 v[138:139], off
	v_lshl_add_u64 v[138:139], s[4:5], 0, v[128:129]
	s_add_i32 m0, s6, 0x2000
	s_nop 0
	global_load_lds_dwordx4 v[138:139], off
	s_waitcnt vmcnt(6)
	s_barrier
	s_setprio 1
	v_mfma_f32_16x16x32_bf16 v[52:55], v[194:197], v[158:161], v[52:55]
	v_mfma_f32_16x16x32_bf16 v[48:51], v[216:219], v[158:161], v[48:51]
	v_mfma_f32_16x16x32_bf16 v[36:39], v[194:197], v[166:169], v[36:39]
	v_mfma_f32_16x16x32_bf16 v[32:35], v[216:219], v[166:169], v[32:35]
	v_mfma_f32_16x16x32_bf16 v[20:23], v[194:197], v[174:177], v[20:23]
	v_mfma_f32_16x16x32_bf16 v[16:19], v[216:219], v[174:177], v[16:19]
	v_mfma_f32_16x16x32_bf16 v[4:7], v[194:197], v[182:185], v[4:7]
	v_mfma_f32_16x16x32_bf16 v[0:3], v[216:219], v[182:185], v[0:3]
	v_mfma_f32_16x16x32_bf16 v[52:55], v[198:201], v[162:165], v[52:55]
	v_mfma_f32_16x16x32_bf16 v[48:51], v[220:223], v[162:165], v[48:51]
	v_mfma_f32_16x16x32_bf16 v[36:39], v[198:201], v[170:173], v[36:39]
	v_mfma_f32_16x16x32_bf16 v[32:35], v[220:223], v[170:173], v[32:35]
	v_mfma_f32_16x16x32_bf16 v[20:23], v[198:201], v[178:181], v[20:23]
	v_mfma_f32_16x16x32_bf16 v[16:19], v[220:223], v[178:181], v[16:19]
	v_mfma_f32_16x16x32_bf16 v[4:7], v[198:201], v[190:193], v[4:7]
	v_mfma_f32_16x16x32_bf16 v[0:3], v[220:223], v[190:193], v[0:3]
	s_setprio 0
	s_add_i32 s35, s35, 2
	s_add_u32 s2, s2, 0x100
	s_addc_u32 s3, s3, 0
	s_add_u32 s22, s22, 0x100
	s_addc_u32 s23, s23, 0
	s_cmp_gt_u32 s35, 13
	s_barrier
	s_cbranch_scc0 .LBB0_372
	v_and_b32_e32 v230, 16, v204
	v_lshrrev_b32_e32 v231, 1, v230
	v_add_u32_e32 v230, v230, v231
	v_mov_b32_e32 v231, v189
	s_lshl_b32 s35, s9, 8
	s_add_i32 s35, s35, s29
	s_lshl_b32 s2, s8, 8
	s_or_b32 s2, s2, s30
	s_ashr_i32 s3, s35, 12
	s_and_b32 s36, s3, -2
	v_or_b32_e32 v138, s2, v132
	s_movk_i32 s3, 0x49f
	v_bitop3_b32 v146, s35, v211, v142 bitop3:0xc8
	v_cmp_lt_i32_e64 s[4:5], s3, v138
	s_and_saveexec_b64 s[6:7], s[4:5]
	s_xor_b64 s[6:7], exec, s[6:7]
	s_cbranch_execz .LBB0_376
	s_cmpk_gt_u32 s2, 0x51f
	s_cbranch_scc1 .LBB0_376
	v_add_u32_e32 v139, 0xfffffb60, v138
	v_lshrrev_b32_e32 v140, 6, v139
	v_add_u32_e32 v140, s36, v140
	v_ashrrev_i32_e32 v141, 31, v140
	v_lshlrev_b64 v[140:141], 20, v[140:141]
	v_lshlrev_b32_e32 v139, 14, v139
	v_lshl_add_u64 v[140:141], s[90:91], 0, v[140:141]
	v_and_b32_e32 v188, 0xb0000, v139
	v_lshl_add_u64 v[140:141], v[140:141], 0, v[188:189]
	v_lshlrev_b32_e32 v188, 1, v146
	v_lshl_add_u64 v[140:141], v[140:141], 0, v[188:189]
	s_movk_i32 s3, 0x4000
	v_cvt_pk_bf16_f32 v139, v124, s0
	v_add_co_u32_e32 v148, vcc, s3, v140
	global_store_short v[140:141], v139, off
	v_cvt_pk_bf16_f32 v139, v125, s0
	v_addc_co_u32_e32 v149, vcc, 0, v141, vcc
	global_store_short v[148:149], v139, off
	v_add_co_u32_e32 v148, vcc, 0x8000, v140
	v_cvt_pk_bf16_f32 v139, v126, s0
	s_nop 0
	v_addc_co_u32_e32 v149, vcc, 0, v141, vcc
	v_add_co_u32_e32 v140, vcc, 0xc000, v140
	global_store_short v[148:149], v139, off
	v_cvt_pk_bf16_f32 v139, v127, s0
	v_addc_co_u32_e32 v141, vcc, 0, v141, vcc
	global_store_short v[140:141], v139, off
.LBB0_376:
	s_or_saveexec_b64 s[6:7], s[6:7]
	v_or_b32_e32 v145, s35, v142
	v_mad_i64_i32 v[140:141], s[8:9], v145, s84, 0
	v_lshl_add_u64 v[140:141], s[88:89], 0, v[140:141]
	v_ashrrev_i32_e32 v139, 31, v138
	s_xor_b64 exec, exec, s[6:7]
	s_cbranch_execz .LBB0_378
	v_cvt_pk_bf16_f32 v124, v124, v125
	v_cvt_pk_bf16_f32 v125, v126, v127
	v_lshl_add_u64 v[126:127], v[138:139], 1, v[140:141]
	v_mov_b64_e32 v[236:237], v[124:125]

.LBB0_381:
	s_andn2_saveexec_b64 s[6:7], s[6:7]
	s_cbranch_execz .LBB0_383
	v_cvt_pk_bf16_f32 v120, v120, v121
	v_cvt_pk_bf16_f32 v121, v122, v123
	v_lshl_add_u64 v[122:123], v[138:139], 1, v[140:141]
	v_mov_b64_e32 v[238:239], v[120:121]
	s_nop 1
	v_permlane16_swap_b32 v236, v238
	v_permlane16_swap_b32 v237, v239
	v_lshl_add_u64 v[248:249], v[122:123], 0, v[230:231]
	global_store_dwordx4 v[248:249], v[236:239], off
	s_nop 1

.LBB0_386:
	s_andn2_saveexec_b64 s[8:9], s[8:9]
	s_cbranch_execz .LBB0_388
	s_ashr_i32 s3, s2, 31
	v_cvt_pk_bf16_f32 v116, v116, v117
	v_cvt_pk_bf16_f32 v117, v118, v119
	v_lshl_add_u64 v[118:119], s[2:3], 0, v[132:133]
	v_lshl_add_u64 v[118:119], v[118:119], 1, v[140:141]
	v_mov_b64_e32 v[232:233], v[116:117]

.LBB0_391:
	s_andn2_saveexec_b64 s[22:23], s[22:23]
	s_cbranch_execz .LBB0_393
	s_ashr_i32 s3, s2, 31
	v_cvt_pk_bf16_f32 v112, v112, v113
	v_cvt_pk_bf16_f32 v113, v114, v115
	v_lshl_add_u64 v[114:115], s[2:3], 0, v[132:133]
	v_lshl_add_u64 v[114:115], v[114:115], 1, v[140:141]
	v_mov_b64_e32 v[234:235], v[112:113]
	s_nop 1
	v_permlane16_swap_b32 v232, v234
	v_permlane16_swap_b32 v233, v235
	v_lshl_add_u64 v[248:249], v[114:115], 0, v[230:231]
	global_store_dwordx4 v[248:249], v[232:235], off offset:256
	s_nop 1

.LBB0_396:
	s_or_saveexec_b64 s[22:23], s[22:23]
	v_or_b32_e32 v112, 16, v145
	v_mad_i64_i32 v[112:113], s[38:39], v112, s84, 0
	v_lshl_add_u64 v[112:113], s[88:89], 0, v[112:113]
	s_xor_b64 exec, exec, s[22:23]
	s_cbranch_execz .LBB0_398
	v_cvt_pk_bf16_f32 v108, v108, v109
	v_cvt_pk_bf16_f32 v109, v110, v111
	v_lshl_add_u64 v[110:111], v[138:139], 1, v[112:113]
	v_mov_b64_e32 v[236:237], v[108:109]

.LBB0_401:
	s_andn2_saveexec_b64 s[22:23], s[22:23]
	s_cbranch_execz .LBB0_403
	v_cvt_pk_bf16_f32 v104, v104, v105
	v_cvt_pk_bf16_f32 v105, v106, v107
	v_lshl_add_u64 v[106:107], v[138:139], 1, v[112:113]
	v_mov_b64_e32 v[238:239], v[104:105]
	s_nop 1
	v_permlane16_swap_b32 v236, v238
	v_permlane16_swap_b32 v237, v239
	v_lshl_add_u64 v[248:249], v[106:107], 0, v[230:231]
	global_store_dwordx4 v[248:249], v[236:239], off
	s_nop 1

.LBB0_406:
	s_andn2_saveexec_b64 s[22:23], s[22:23]
	s_cbranch_execz .LBB0_408
	s_ashr_i32 s3, s2, 31
	v_cvt_pk_bf16_f32 v100, v100, v101
	v_cvt_pk_bf16_f32 v101, v102, v103
	v_lshl_add_u64 v[102:103], s[2:3], 0, v[132:133]
	v_lshl_add_u64 v[102:103], v[102:103], 1, v[112:113]
	v_mov_b64_e32 v[232:233], v[100:101]

.LBB0_411:
	s_andn2_saveexec_b64 s[22:23], s[22:23]
	s_cbranch_execz .LBB0_413
	s_ashr_i32 s3, s2, 31
	v_cvt_pk_bf16_f32 v96, v96, v97
	v_cvt_pk_bf16_f32 v97, v98, v99
	v_lshl_add_u64 v[98:99], s[2:3], 0, v[132:133]
	v_lshl_add_u64 v[98:99], v[98:99], 1, v[112:113]
	v_mov_b64_e32 v[234:235], v[96:97]
	s_nop 1
	v_permlane16_swap_b32 v232, v234
	v_permlane16_swap_b32 v233, v235
	v_lshl_add_u64 v[248:249], v[98:99], 0, v[230:231]
	global_store_dwordx4 v[248:249], v[232:235], off offset:256
	s_nop 1

.LBB0_416:
	s_or_saveexec_b64 s[22:23], s[22:23]
	v_or_b32_e32 v96, 32, v145
	v_mad_i64_i32 v[96:97], s[38:39], v96, s84, 0
	v_lshl_add_u64 v[96:97], s[88:89], 0, v[96:97]
	s_xor_b64 exec, exec, s[22:23]
	s_cbranch_execz .LBB0_418
	v_cvt_pk_bf16_f32 v92, v92, v93
	v_cvt_pk_bf16_f32 v93, v94, v95
	v_lshl_add_u64 v[94:95], v[138:139], 1, v[96:97]
	v_mov_b64_e32 v[236:237], v[92:93]

.LBB0_421:
	s_andn2_saveexec_b64 s[22:23], s[22:23]
	s_cbranch_execz .LBB0_423
	v_cvt_pk_bf16_f32 v88, v88, v89
	v_cvt_pk_bf16_f32 v89, v90, v91
	v_lshl_add_u64 v[90:91], v[138:139], 1, v[96:97]
	v_mov_b64_e32 v[238:239], v[88:89]
	s_nop 1
	v_permlane16_swap_b32 v236, v238
	v_permlane16_swap_b32 v237, v239
	v_lshl_add_u64 v[248:249], v[90:91], 0, v[230:231]
	global_store_dwordx4 v[248:249], v[236:239], off
	s_nop 1

.LBB0_426:
	s_andn2_saveexec_b64 s[22:23], s[22:23]
	s_cbranch_execz .LBB0_428
	s_ashr_i32 s3, s2, 31
	v_cvt_pk_bf16_f32 v84, v84, v85
	v_cvt_pk_bf16_f32 v85, v86, v87
	v_lshl_add_u64 v[86:87], s[2:3], 0, v[132:133]
	v_lshl_add_u64 v[86:87], v[86:87], 1, v[96:97]
	v_mov_b64_e32 v[232:233], v[84:85]

.LBB0_431:
	s_andn2_saveexec_b64 s[22:23], s[22:23]
	s_cbranch_execz .LBB0_433
	s_ashr_i32 s3, s2, 31
	v_cvt_pk_bf16_f32 v80, v80, v81
	v_cvt_pk_bf16_f32 v81, v82, v83
	v_lshl_add_u64 v[82:83], s[2:3], 0, v[132:133]
	v_lshl_add_u64 v[82:83], v[82:83], 1, v[96:97]
	v_mov_b64_e32 v[234:235], v[80:81]
	s_nop 1
	v_permlane16_swap_b32 v232, v234
	v_permlane16_swap_b32 v233, v235
	v_lshl_add_u64 v[248:249], v[82:83], 0, v[230:231]
	global_store_dwordx4 v[248:249], v[232:235], off offset:256
	s_nop 1

.LBB0_436:
	s_or_saveexec_b64 s[22:23], s[22:23]
	v_or_b32_e32 v80, 48, v145
	v_mad_i64_i32 v[80:81], s[38:39], v80, s84, 0
	v_lshl_add_u64 v[80:81], s[88:89], 0, v[80:81]
	s_xor_b64 exec, exec, s[22:23]
	s_cbranch_execz .LBB0_438
	v_cvt_pk_bf16_f32 v76, v76, v77
	v_cvt_pk_bf16_f32 v77, v78, v79
	v_lshl_add_u64 v[78:79], v[138:139], 1, v[80:81]
	v_mov_b64_e32 v[236:237], v[76:77]

.LBB0_441:
	s_andn2_saveexec_b64 s[22:23], s[22:23]
	s_cbranch_execz .LBB0_443
	v_cvt_pk_bf16_f32 v72, v72, v73
	v_cvt_pk_bf16_f32 v73, v74, v75
	v_lshl_add_u64 v[74:75], v[138:139], 1, v[80:81]
	v_mov_b64_e32 v[238:239], v[72:73]
	s_nop 1
	v_permlane16_swap_b32 v236, v238
	v_permlane16_swap_b32 v237, v239
	v_lshl_add_u64 v[248:249], v[74:75], 0, v[230:231]
	global_store_dwordx4 v[248:249], v[236:239], off
	s_nop 1

.LBB0_446:
	s_andn2_saveexec_b64 s[22:23], s[22:23]
	s_cbranch_execz .LBB0_448
	s_ashr_i32 s3, s2, 31
	v_cvt_pk_bf16_f32 v68, v68, v69
	v_cvt_pk_bf16_f32 v69, v70, v71
	v_lshl_add_u64 v[70:71], s[2:3], 0, v[132:133]
	v_lshl_add_u64 v[70:71], v[70:71], 1, v[80:81]
	v_mov_b64_e32 v[232:233], v[68:69]

.LBB0_451:
	s_andn2_saveexec_b64 s[22:23], s[22:23]
	s_cbranch_execz .LBB0_453
	s_ashr_i32 s3, s2, 31
	v_cvt_pk_bf16_f32 v64, v64, v65
	v_cvt_pk_bf16_f32 v65, v66, v67
	v_lshl_add_u64 v[66:67], s[2:3], 0, v[132:133]
	v_lshl_add_u64 v[66:67], v[66:67], 1, v[80:81]
	v_mov_b64_e32 v[234:235], v[64:65]
	s_nop 1
	v_permlane16_swap_b32 v232, v234
	v_permlane16_swap_b32 v233, v235
	v_lshl_add_u64 v[248:249], v[66:67], 0, v[230:231]
	global_store_dwordx4 v[248:249], v[232:235], off offset:256
	s_nop 1

.LBB0_456:
	s_or_saveexec_b64 s[22:23], s[22:23]
	v_or_b32_e32 v66, s3, v142
	v_mad_i64_i32 v[64:65], s[36:37], v66, s84, 0
	v_lshl_add_u64 v[64:65], s[88:89], 0, v[64:65]
	s_xor_b64 exec, exec, s[22:23]
	s_cbranch_execz .LBB0_458
	v_cvt_pk_bf16_f32 v60, v60, v61
	v_cvt_pk_bf16_f32 v61, v62, v63
	v_lshl_add_u64 v[62:63], v[138:139], 1, v[64:65]
	v_mov_b64_e32 v[236:237], v[60:61]

.LBB0_461:
	s_andn2_saveexec_b64 s[22:23], s[22:23]
	s_cbranch_execz .LBB0_463
	v_cvt_pk_bf16_f32 v56, v56, v57
	v_cvt_pk_bf16_f32 v57, v58, v59
	v_lshl_add_u64 v[58:59], v[138:139], 1, v[64:65]
	v_mov_b64_e32 v[238:239], v[56:57]
	s_nop 1
	v_permlane16_swap_b32 v236, v238
	v_permlane16_swap_b32 v237, v239
	v_lshl_add_u64 v[248:249], v[58:59], 0, v[230:231]
	global_store_dwordx4 v[248:249], v[236:239], off
	s_nop 1

.LBB0_466:
	s_andn2_saveexec_b64 s[22:23], s[22:23]
	s_cbranch_execz .LBB0_468
	s_ashr_i32 s3, s2, 31
	v_cvt_pk_bf16_f32 v52, v52, v53
	v_cvt_pk_bf16_f32 v53, v54, v55
	v_lshl_add_u64 v[54:55], s[2:3], 0, v[132:133]
	v_lshl_add_u64 v[54:55], v[54:55], 1, v[64:65]
	v_mov_b64_e32 v[232:233], v[52:53]

.LBB0_471:
	s_andn2_saveexec_b64 s[22:23], s[22:23]
	s_cbranch_execz .LBB0_473
	s_ashr_i32 s3, s2, 31
	v_cvt_pk_bf16_f32 v48, v48, v49
	v_cvt_pk_bf16_f32 v49, v50, v51
	v_lshl_add_u64 v[50:51], s[2:3], 0, v[132:133]
	v_lshl_add_u64 v[50:51], v[50:51], 1, v[64:65]
	v_mov_b64_e32 v[234:235], v[48:49]
	s_nop 1
	v_permlane16_swap_b32 v232, v234
	v_permlane16_swap_b32 v233, v235
	v_lshl_add_u64 v[248:249], v[50:51], 0, v[230:231]
	global_store_dwordx4 v[248:249], v[232:235], off offset:256
	s_nop 1

.LBB0_476:
	s_or_saveexec_b64 s[22:23], s[22:23]
	v_or_b32_e32 v48, 16, v66
	v_mad_i64_i32 v[48:49], s[36:37], v48, s84, 0
	v_lshl_add_u64 v[48:49], s[88:89], 0, v[48:49]
	s_xor_b64 exec, exec, s[22:23]
	s_cbranch_execz .LBB0_478
	v_cvt_pk_bf16_f32 v44, v44, v45
	v_cvt_pk_bf16_f32 v45, v46, v47
	v_lshl_add_u64 v[46:47], v[138:139], 1, v[48:49]
	v_mov_b64_e32 v[236:237], v[44:45]

.LBB0_481:
	s_andn2_saveexec_b64 s[22:23], s[22:23]
	s_cbranch_execz .LBB0_483
	v_cvt_pk_bf16_f32 v40, v40, v41
	v_cvt_pk_bf16_f32 v41, v42, v43
	v_lshl_add_u64 v[42:43], v[138:139], 1, v[48:49]
	v_mov_b64_e32 v[238:239], v[40:41]
	s_nop 1
	v_permlane16_swap_b32 v236, v238
	v_permlane16_swap_b32 v237, v239
	v_lshl_add_u64 v[248:249], v[42:43], 0, v[230:231]
	global_store_dwordx4 v[248:249], v[236:239], off
	s_nop 1

.LBB0_486:
	s_andn2_saveexec_b64 s[22:23], s[22:23]
	s_cbranch_execz .LBB0_488
	s_ashr_i32 s3, s2, 31
	v_cvt_pk_bf16_f32 v36, v36, v37
	v_cvt_pk_bf16_f32 v37, v38, v39
	v_lshl_add_u64 v[38:39], s[2:3], 0, v[132:133]
	v_lshl_add_u64 v[38:39], v[38:39], 1, v[48:49]
	v_mov_b64_e32 v[232:233], v[36:37]

.LBB0_491:
	s_andn2_saveexec_b64 s[22:23], s[22:23]
	s_cbranch_execz .LBB0_493
	s_ashr_i32 s3, s2, 31
	v_cvt_pk_bf16_f32 v32, v32, v33
	v_cvt_pk_bf16_f32 v33, v34, v35
	v_lshl_add_u64 v[34:35], s[2:3], 0, v[132:133]
	v_lshl_add_u64 v[34:35], v[34:35], 1, v[48:49]
	v_mov_b64_e32 v[234:235], v[32:33]
	s_nop 1
	v_permlane16_swap_b32 v232, v234
	v_permlane16_swap_b32 v233, v235
	v_lshl_add_u64 v[248:249], v[34:35], 0, v[230:231]
	global_store_dwordx4 v[248:249], v[232:235], off offset:256
	s_nop 1

.LBB0_496:
	s_or_saveexec_b64 s[22:23], s[22:23]
	v_or_b32_e32 v32, 32, v66
	v_mad_i64_i32 v[32:33], s[36:37], v32, s84, 0
	v_lshl_add_u64 v[32:33], s[88:89], 0, v[32:33]
	s_xor_b64 exec, exec, s[22:23]
	s_cbranch_execz .LBB0_498
	v_cvt_pk_bf16_f32 v28, v28, v29
	v_cvt_pk_bf16_f32 v29, v30, v31
	v_lshl_add_u64 v[30:31], v[138:139], 1, v[32:33]
	v_mov_b64_e32 v[236:237], v[28:29]

.LBB0_501:
	s_andn2_saveexec_b64 s[22:23], s[22:23]
	s_cbranch_execz .LBB0_503
	v_cvt_pk_bf16_f32 v24, v24, v25
	v_cvt_pk_bf16_f32 v25, v26, v27
	v_lshl_add_u64 v[26:27], v[138:139], 1, v[32:33]
	v_mov_b64_e32 v[238:239], v[24:25]
	s_nop 1
	v_permlane16_swap_b32 v236, v238
	v_permlane16_swap_b32 v237, v239
	v_lshl_add_u64 v[248:249], v[26:27], 0, v[230:231]
	global_store_dwordx4 v[248:249], v[236:239], off
	s_nop 1

.LBB0_506:
	s_andn2_saveexec_b64 s[22:23], s[22:23]
	s_cbranch_execz .LBB0_508
	s_ashr_i32 s3, s2, 31
	v_cvt_pk_bf16_f32 v20, v20, v21
	v_cvt_pk_bf16_f32 v21, v22, v23
	v_lshl_add_u64 v[22:23], s[2:3], 0, v[132:133]
	v_lshl_add_u64 v[22:23], v[22:23], 1, v[32:33]
	v_mov_b64_e32 v[232:233], v[20:21]

.LBB0_511:
	s_andn2_saveexec_b64 s[22:23], s[22:23]
	s_cbranch_execz .LBB0_513
	s_ashr_i32 s3, s2, 31
	v_cvt_pk_bf16_f32 v16, v16, v17
	v_cvt_pk_bf16_f32 v17, v18, v19
	v_lshl_add_u64 v[18:19], s[2:3], 0, v[132:133]
	v_lshl_add_u64 v[18:19], v[18:19], 1, v[32:33]
	v_mov_b64_e32 v[234:235], v[16:17]
	s_nop 1
	v_permlane16_swap_b32 v232, v234
	v_permlane16_swap_b32 v233, v235
	v_lshl_add_u64 v[248:249], v[18:19], 0, v[230:231]
	global_store_dwordx4 v[248:249], v[232:235], off offset:256
	s_nop 1

.LBB0_516:
	s_or_saveexec_b64 s[4:5], s[4:5]
	v_or_b32_e32 v16, 48, v66
	v_mad_i64_i32 v[16:17], s[22:23], v16, s84, 0
	v_lshl_add_u64 v[16:17], s[88:89], 0, v[16:17]
	s_xor_b64 exec, exec, s[4:5]
	s_cbranch_execz .LBB0_518
	v_cvt_pk_bf16_f32 v12, v12, v13
	v_cvt_pk_bf16_f32 v13, v14, v15
	v_lshl_add_u64 v[14:15], v[138:139], 1, v[16:17]
	v_mov_b64_e32 v[236:237], v[12:13]

.LBB0_521:
	s_andn2_saveexec_b64 s[4:5], s[4:5]
	s_cbranch_execz .LBB0_523
	v_cvt_pk_bf16_f32 v8, v8, v9
	v_cvt_pk_bf16_f32 v9, v10, v11
	v_lshl_add_u64 v[10:11], v[138:139], 1, v[16:17]
	v_mov_b64_e32 v[238:239], v[8:9]
	s_nop 1
	v_permlane16_swap_b32 v236, v238
	v_permlane16_swap_b32 v237, v239
	v_lshl_add_u64 v[248:249], v[10:11], 0, v[230:231]
	global_store_dwordx4 v[248:249], v[236:239], off
	s_nop 1

.LBB0_526:
	s_andn2_saveexec_b64 s[4:5], s[4:5]
	s_cbranch_execz .LBB0_528
	s_ashr_i32 s3, s2, 31
	v_cvt_pk_bf16_f32 v4, v4, v5
	v_cvt_pk_bf16_f32 v5, v6, v7
	v_lshl_add_u64 v[6:7], s[2:3], 0, v[132:133]
	v_lshl_add_u64 v[6:7], v[6:7], 1, v[16:17]
	v_mov_b64_e32 v[232:233], v[4:5]

.LBB0_531:
	s_andn2_saveexec_b64 s[4:5], s[4:5]
	s_cbranch_execz .LBB0_368
	s_ashr_i32 s3, s2, 31
	v_cvt_pk_bf16_f32 v0, v0, v1
	v_cvt_pk_bf16_f32 v1, v2, v3
	v_lshl_add_u64 v[2:3], s[2:3], 0, v[132:133]
	v_lshl_add_u64 v[2:3], v[2:3], 1, v[16:17]
	v_mov_b64_e32 v[234:235], v[0:1]
	s_nop 1
	v_permlane16_swap_b32 v232, v234
	v_permlane16_swap_b32 v233, v235
	v_lshl_add_u64 v[248:249], v[2:3], 0, v[230:231]
	global_store_dwordx4 v[248:249], v[232:235], off offset:256
	s_nop 1
	s_branch .LBB0_368
